# global_* memory ops; SSQ atomics of the residual epilogues (FFN1-down, out-proj) collected and issued at the end of the tile epilogue
# baseline (speedup 1.0000x reference)
; __device__ __forceinline__ unsigned cvt_pk_bf16(float lo, float hi) { unsigned r; asm volatile("v_cvt_pk_bf16_f32 %0, %1, %2" : "=v"(r) : "v"(lo), "v"(hi)); return r; }
;     __device__ __forceinline__ void operator()(const f32x4 (&acc)[2][2][4][2], const Unit& u, int wr, int wc, int fr_, int fq_) const {
;     ...
;         for (int mh = 0; mh < 2; ++mh) {
;             f32x4 bs[2][2][2];
; #pragma unroll
;             for (int m = 0; m < 2; ++m) { const size_t off = (size_t)(row0 + ai * HALF + (2 * mh + m) * 16) * ldc + col0;
; #pragma unroll
;                 for (int bj = 0; bj < 2; ++bj)
; #pragma unroll
;                     for (int n = 0; n < 2; ++n) bs[m][bj][n] = *(const f32x4*)(base + off + bj * HALF + n * 16); }
;             asm volatile("" ::: "memory");
; #pragma unroll
;             for (int m = 0; m < 2; ++m) { const int row = row0 + ai * HALF + (2 * mh + m) * 16; const size_t off = (size_t)row * ldc + col0; float ss = 0.f;
; #pragma unroll
;                 for (int bj = 0; bj < 2; ++bj)
; #pragma unroll
;                     for (int n = 0; n < 2; ++n) { const f32x4 o = bs[m][bj][n] + gv[bj][n] * acc[ai][bj][2 * mh + m][n]; *(f32x4*)(out + off + bj * HALF + n * 16) = o;
;                         if constexpr (EMIT) { ss += (o[0] * o[0] + o[1] * o[1]) + (o[2] * o[2] + o[3] * o[3]); const f32x4 y = o * gm[bj][n];
;                             typedef unsigned u32x2_t __attribute__((ext_vector_type(2))); u32x2_t w; w.x = cvt_pk_bf16(y[0], y[1]); w.y = cvt_pk_bf16(y[2], y[3]); *(u32x2_t*)(A2 + off + bj * HALF + n * 16) = w; } }
;                 if constexpr (EMIT) { ss += __shfl_xor(ss, 16); ss += __shfl_xor(ss, 32); if (fq == 0) atomicAdd(ssq + row, (unsigned long long)(ss * 16777216.0f)); } }
.LBB0_500:
	v_mbcnt_lo_u32_b32 v201, -1, 0
	v_mbcnt_hi_u32_b32 v201, -1, v201
	s_lshl_b32 s5, s57, 8
	v_ashrrev_i32_e32 v64, 2, v201
	s_lshl_b32 s4, s58, 8
	s_or_b32 s5, s5, s47
	v_and_b32_e32 v64, -4, v64
	s_add_i32 s4, s4, s46
	v_add_u32_e32 v188, s5, v64
	v_ashrrev_i32_e32 v189, 31, v188
	v_and_or_b32 v192, v201, 15, s4
	v_lshlrev_b64 v[64:65], 2, v[188:189]
	v_ashrrev_i32_e32 v193, 31, v192
	v_lshl_add_u64 v[190:191], s[8:9], 0, v[64:65]
	v_lshlrev_b64 v[72:73], 13, v[192:193]
	v_lshl_add_u64 v[80:81], v[190:191], 0, v[72:73]
	v_lshl_add_u64 v[66:67], s[14:15], 0, v[64:65]
	global_load_dwordx4 v[202:205], v[80:81], off
	global_load_dwordx4 v[104:107], v[66:67], off
	global_load_dwordx4 v[92:95], v[66:67], off offset:64
	global_load_dwordx4 v[206:209], v[80:81], off offset:64
	global_load_dwordx4 v[210:213], v[80:81], off offset:512
	global_load_dwordx4 v[84:87], v[66:67], off offset:512
	global_load_dwordx4 v[72:75], v[66:67], off offset:576
	global_load_dwordx4 v[214:217], v[80:81], off offset:576
	v_lshl_add_u64 v[64:65], s[18:19], 0, v[64:65]
	global_load_dwordx4 v[100:103], v[64:65], off
	global_load_dwordx4 v[88:91], v[64:65], off offset:64
	global_load_dwordx4 v[80:83], v[64:65], off offset:512
	s_nop 0
	global_load_dwordx4 v[64:67], v[64:65], off offset:576
	v_or_b32_e32 v194, 16, v192
	v_ashrrev_i32_e32 v195, 31, v194
	v_lshlrev_b64 v[160:161], 13, v[194:195]
	v_lshl_add_u64 v[160:161], v[190:191], 0, v[160:161]
	global_load_dwordx4 v[172:175], v[160:161], off
	global_load_dwordx4 v[168:171], v[160:161], off offset:64
	global_load_dwordx4 v[164:167], v[160:161], off offset:512
	s_nop 0
	global_load_dwordx4 v[160:163], v[160:161], off offset:576
	v_and_b32_e32 v219, 64, v200
	v_xor_b32_e32 v218, 16, v200
	v_cmp_gt_u32_e32 vcc, 16, v201
	v_add_u32_e32 v201, 64, v219
	v_cmp_lt_i32_e64 s[4:5], v218, v201
	s_waitcnt vmcnt(0) lgkmcnt(0)
	v_pk_fma_f32 v[158:159], v[158:159], v[106:107], v[204:205]
	v_cndmask_b32_e64 v222, v200, v218, s[4:5]
	v_lshlrev_b64 v[218:219], 11, v[192:193]
	v_lshl_add_u64 v[218:219], v[218:219], 0, v[188:189]
	v_lshl_add_u64 v[220:221], v[218:219], 2, s[10:11]
	v_pk_fma_f32 v[156:157], v[156:157], v[104:105], v[202:203]
	v_pk_fma_f32 v[154:155], v[154:155], v[94:95], v[208:209]
	v_pk_fma_f32 v[152:153], v[152:153], v[92:93], v[206:207]
	v_pk_fma_f32 v[150:151], v[150:151], v[86:87], v[212:213]
	v_pk_fma_f32 v[148:149], v[148:149], v[84:85], v[210:211]
	v_pk_fma_f32 v[204:205], v[146:147], v[74:75], v[216:217]
	v_pk_fma_f32 v[202:203], v[144:145], v[72:73], v[214:215]
	global_store_dwordx4 v[220:221], v[156:159], off
	v_mul_f32_e32 v214, v157, v157
	v_mul_f32_e32 v215, v159, v159
	v_pk_mul_f32 v[144:145], v[102:103], v[158:159]
	v_pk_mul_f32 v[146:147], v[100:101], v[156:157]
	v_mul_f32_e32 v157, v153, v153
	v_mul_f32_e32 v159, v155, v155
	v_lshl_add_u64 v[218:219], v[218:219], 1, s[16:17]
	v_mul_f32_e32 v216, v149, v149
	v_mul_f32_e32 v217, v151, v151
	v_fmac_f32_e32 v214, v156, v156
	v_fmac_f32_e32 v215, v158, v158
	v_cvt_pk_bf16_f32 v146, v146, v147
	v_cvt_pk_bf16_f32 v147, v144, v145
	v_fmac_f32_e32 v157, v152, v152
	v_fmac_f32_e32 v159, v154, v154
	v_mul_f32_e32 v223, v203, v203
	v_mul_f32_e32 v224, v205, v205
	v_fmac_f32_e32 v216, v148, v148
	v_fmac_f32_e32 v217, v150, v150
	v_add_f32_e32 v156, v214, v215
	global_store_dwordx2 v[218:219], v[146:147], off
	global_store_dwordx4 v[220:221], v[152:155], off offset:64
	v_add_f32_e32 v146, v157, v159
	v_pk_mul_f32 v[206:207], v[90:91], v[154:155]
	v_pk_mul_f32 v[208:209], v[88:89], v[152:153]
	v_fmac_f32_e32 v223, v202, v202
	v_fmac_f32_e32 v224, v204, v204
	v_cvt_pk_bf16_f32 v144, v208, v209
	v_cvt_pk_bf16_f32 v145, v206, v207
	v_add_f32_e32 v147, v216, v217
	v_add_f32_e32 v146, v156, v146
	v_add_f32_e32 v152, v223, v224
	global_store_dwordx2 v[218:219], v[144:145], off offset:32
	global_store_dwordx4 v[220:221], v[148:151], off offset:512
	v_add_f32_e32 v145, v146, v147
	v_pk_mul_f32 v[212:213], v[80:81], v[148:149]
	v_add_f32_e32 v149, v145, v152
	v_lshlrev_b32_e32 v148, 2, v222
	v_pk_mul_f32 v[210:211], v[82:83], v[150:151]
	ds_bpermute_b32 v150, v148, v149
	v_cvt_pk_bf16_f32 v144, v212, v213
	v_cvt_pk_bf16_f32 v145, v210, v211
	global_store_dwordx2 v[218:219], v[144:145], off offset:256
	global_store_dwordx4 v[220:221], v[202:205], off offset:576
	v_xor_b32_e32 v145, 32, v200
	v_cmp_lt_i32_e64 s[4:5], v145, v201
	s_waitcnt lgkmcnt(0)
	v_add_f32_e32 v144, v149, v150
	v_pk_mul_f32 v[150:151], v[64:65], v[202:203]
	v_cndmask_b32_e64 v145, v200, v145, s[4:5]
	v_lshlrev_b32_e32 v149, 2, v145
	ds_bpermute_b32 v145, v149, v144
	v_pk_mul_f32 v[146:147], v[66:67], v[204:205]
	v_cvt_pk_bf16_f32 v150, v150, v151
	s_nop 0
	v_cvt_pk_bf16_f32 v151, v146, v147
	global_store_dwordx2 v[218:219], v[150:151], off offset:288
	s_and_saveexec_b64 s[4:5], vcc
	s_cbranch_execz .LBB0_502
	s_waitcnt lgkmcnt(0)
	v_add_f32_e32 v144, v144, v145
	v_mul_f32_e32 v144, 0x4b800000, v144
	v_trunc_f32_e32 v144, v144
	v_mul_f32_e32 v145, 0x2f800000, v144
	v_floor_f32_e32 v145, v145
	v_fmac_f32_e32 v144, 0xcf800000, v145
	v_cvt_u32_f32_e32 v144, v144
	v_cvt_u32_f32_e32 v145, v145
	v_mov_b32_e32 v226, v144
	v_mov_b32_e32 v227, v145
	v_lshl_add_u64 v[242:243], v[192:193], 3, s[20:21]
; __device__ __forceinline__ unsigned cvt_pk_bf16(float lo, float hi) { unsigned r; asm volatile("v_cvt_pk_bf16_f32 %0, %1, %2" : "=v"(r) : "v"(lo), "v"(hi)); return r; }
;     __device__ __forceinline__ void operator()(const f32x4 (&acc)[2][2][4][2], const Unit& u, int wr, int wc, int fr_, int fq_) const {
;     ...
;             for (int m = 0; m < 2; ++m) { const size_t off = (size_t)(row0 + ai * HALF + (2 * mh + m) * 16) * ldc + col0;
; #pragma unroll
;                 for (int bj = 0; bj < 2; ++bj)
; #pragma unroll
;                     for (int n = 0; n < 2; ++n) bs[m][bj][n] = *(const f32x4*)(base + off + bj * HALF + n * 16); }
;             asm volatile("" ::: "memory");
; #pragma unroll
;             for (int m = 0; m < 2; ++m) { const int row = row0 + ai * HALF + (2 * mh + m) * 16; const size_t off = (size_t)row * ldc + col0; float ss = 0.f;
; #pragma unroll
;                 for (int bj = 0; bj < 2; ++bj)
; #pragma unroll
;                     for (int n = 0; n < 2; ++n) { const f32x4 o = bs[m][bj][n] + gv[bj][n] * acc[ai][bj][2 * mh + m][n]; *(f32x4*)(out + off + bj * HALF + n * 16) = o;
;                         if constexpr (EMIT) { ss += (o[0] * o[0] + o[1] * o[1]) + (o[2] * o[2] + o[3] * o[3]); const f32x4 y = o * gm[bj][n];
;                             typedef unsigned u32x2_t __attribute__((ext_vector_type(2))); u32x2_t w; w.x = cvt_pk_bf16(y[0], y[1]); w.y = cvt_pk_bf16(y[2], y[3]); *(u32x2_t*)(A2 + off + bj * HALF + n * 16) = w; } }
;                 if constexpr (EMIT) { ss += __shfl_xor(ss, 16); ss += __shfl_xor(ss, 32); if (fq == 0) atomicAdd(ssq + row, (unsigned long long)(ss * 16777216.0f)); } }
.LBB0_502:
	s_or_b64 exec, exec, s[4:5]
	s_waitcnt lgkmcnt(0)
	v_lshlrev_b64 v[144:145], 11, v[194:195]
	v_lshl_add_u64 v[144:145], v[144:145], 0, v[188:189]
	v_pk_fma_f32 v[142:143], v[142:143], v[106:107], v[174:175]
	v_pk_fma_f32 v[140:141], v[140:141], v[104:105], v[172:173]
	v_lshl_add_u64 v[146:147], v[144:145], 2, s[10:11]
	v_mul_f32_e32 v150, v141, v141
	v_mul_f32_e32 v151, v143, v143
	global_store_dwordx4 v[146:147], v[140:143], off
	v_fmac_f32_e32 v150, v140, v140
	v_fmac_f32_e32 v151, v142, v142
	v_pk_mul_f32 v[142:143], v[102:103], v[142:143]
	v_pk_mul_f32 v[140:141], v[100:101], v[140:141]
	v_pk_fma_f32 v[136:137], v[136:137], v[92:93], v[168:169]
	v_cvt_pk_bf16_f32 v140, v140, v141
	v_cvt_pk_bf16_f32 v141, v142, v143
	v_lshl_add_u64 v[142:143], v[144:145], 1, s[16:17]
	global_store_dwordx2 v[142:143], v[140:141], off
	v_pk_fma_f32 v[138:139], v[138:139], v[94:95], v[170:171]
	v_mul_f32_e32 v140, v137, v137
	global_store_dwordx4 v[146:147], v[136:139], off offset:64
	v_fmac_f32_e32 v140, v136, v136
	v_mul_f32_e32 v141, v139, v139
	v_pk_mul_f32 v[136:137], v[88:89], v[136:137]
	v_fmac_f32_e32 v141, v138, v138
	v_pk_mul_f32 v[138:139], v[90:91], v[138:139]
	v_cvt_pk_bf16_f32 v136, v136, v137
	v_pk_fma_f32 v[134:135], v[134:135], v[86:87], v[166:167]
	v_cvt_pk_bf16_f32 v137, v138, v139
	v_pk_fma_f32 v[132:133], v[132:133], v[84:85], v[164:165]
	global_store_dwordx2 v[142:143], v[136:137], off offset:32
	v_mul_f32_e32 v136, v133, v133
	v_mul_f32_e32 v137, v135, v135
	v_add_f32_e32 v150, v150, v151
	v_add_f32_e32 v140, v140, v141
	v_fmac_f32_e32 v136, v132, v132
	v_fmac_f32_e32 v137, v134, v134
	v_add_f32_e32 v140, v150, v140
	global_store_dwordx4 v[146:147], v[132:135], off offset:512
	v_add_f32_e32 v136, v136, v137
	v_add_f32_e32 v137, v140, v136
	v_pk_mul_f32 v[132:133], v[80:81], v[132:133]
	v_pk_mul_f32 v[134:135], v[82:83], v[134:135]
	v_cvt_pk_bf16_f32 v136, v132, v133
	v_pk_fma_f32 v[132:133], v[130:131], v[74:75], v[162:163]
	v_pk_fma_f32 v[130:131], v[128:129], v[72:73], v[160:161]
	v_mul_f32_e32 v129, v133, v133
	v_mul_f32_e32 v128, v131, v131
	v_fmac_f32_e32 v128, v130, v130
	v_fmac_f32_e32 v129, v132, v132
	v_add_f32_e32 v128, v128, v129
	v_add_f32_e32 v128, v137, v128
	ds_bpermute_b32 v129, v148, v128
	v_cvt_pk_bf16_f32 v137, v134, v135
	global_store_dwordx2 v[142:143], v[136:137], off offset:256
	global_store_dwordx4 v[146:147], v[130:133], off offset:576
	s_waitcnt lgkmcnt(0)
	v_add_f32_e32 v128, v128, v129
	ds_bpermute_b32 v129, v149, v128
	v_pk_mul_f32 v[130:131], v[64:65], v[130:131]
	v_pk_mul_f32 v[132:133], v[66:67], v[132:133]
	v_cvt_pk_bf16_f32 v130, v130, v131
	s_nop 0
	v_cvt_pk_bf16_f32 v131, v132, v133
	global_store_dwordx2 v[142:143], v[130:131], off offset:288
	s_and_saveexec_b64 s[4:5], vcc
	s_cbranch_execz .LBB0_504
	s_waitcnt lgkmcnt(0)
	v_add_f32_e32 v128, v128, v129
	v_mul_f32_e32 v128, 0x4b800000, v128
	v_trunc_f32_e32 v128, v128
	v_mul_f32_e32 v129, 0x2f800000, v128
	v_floor_f32_e32 v129, v129
	v_fmac_f32_e32 v128, 0xcf800000, v129
	v_cvt_u32_f32_e32 v128, v128
	v_cvt_u32_f32_e32 v129, v129
	v_mov_b32_e32 v228, v128
	v_mov_b32_e32 v229, v129
.LBB0_504:
	s_or_b64 exec, exec, s[4:5]
	v_or_b32_e32 v146, 32, v192
	v_ashrrev_i32_e32 v147, 31, v146
	s_waitcnt lgkmcnt(0)
	v_lshlrev_b64 v[128:129], 13, v[146:147]
	v_lshl_add_u64 v[128:129], v[190:191], 0, v[128:129]
	global_load_dwordx4 v[150:153], v[128:129], off
	global_load_dwordx4 v[154:157], v[128:129], off offset:64
	global_load_dwordx4 v[158:161], v[128:129], off offset:512
	global_load_dwordx4 v[162:165], v[128:129], off offset:576
	v_or_b32_e32 v144, 48, v192
	v_ashrrev_i32_e32 v145, 31, v144
	v_lshlrev_b64 v[128:129], 13, v[144:145]
	v_lshl_add_u64 v[128:129], v[190:191], 0, v[128:129]
	global_load_dwordx4 v[140:143], v[128:129], off
	global_load_dwordx4 v[136:139], v[128:129], off offset:64
	global_load_dwordx4 v[132:135], v[128:129], off offset:512
	s_nop 0
	global_load_dwordx4 v[128:131], v[128:129], off offset:576
	v_lshlrev_b64 v[166:167], 11, v[146:147]
	v_lshl_add_u64 v[166:167], v[166:167], 0, v[188:189]
	v_lshl_add_u64 v[168:169], v[166:167], 2, s[10:11]
	v_lshl_add_u64 v[166:167], v[166:167], 1, s[16:17]
	s_waitcnt vmcnt(0) lgkmcnt(0)
	v_pk_fma_f32 v[126:127], v[126:127], v[106:107], v[152:153]
	v_pk_fma_f32 v[124:125], v[124:125], v[104:105], v[150:151]
	v_pk_fma_f32 v[122:123], v[122:123], v[94:95], v[156:157]
	v_pk_fma_f32 v[120:121], v[120:121], v[92:93], v[154:155]
	v_pk_fma_f32 v[118:119], v[118:119], v[86:87], v[160:161]
	v_pk_fma_f32 v[116:117], v[116:117], v[84:85], v[158:159]
	v_pk_fma_f32 v[152:153], v[114:115], v[74:75], v[164:165]
	v_pk_fma_f32 v[150:151], v[112:113], v[72:73], v[162:163]
	global_store_dwordx4 v[168:169], v[124:127], off
	v_mul_f32_e32 v162, v125, v125
	v_mul_f32_e32 v163, v127, v127
	v_pk_mul_f32 v[112:113], v[102:103], v[126:127]
	v_pk_mul_f32 v[114:115], v[100:101], v[124:125]
	v_mul_f32_e32 v125, v121, v121
	v_mul_f32_e32 v127, v123, v123
	v_mul_f32_e32 v164, v117, v117
	v_mul_f32_e32 v165, v119, v119
	v_fmac_f32_e32 v162, v124, v124
	v_fmac_f32_e32 v163, v126, v126
	v_cvt_pk_bf16_f32 v114, v114, v115
	v_cvt_pk_bf16_f32 v115, v112, v113
	v_fmac_f32_e32 v125, v120, v120
	v_fmac_f32_e32 v127, v122, v122
	v_mul_f32_e32 v170, v151, v151
	v_mul_f32_e32 v171, v153, v153
	v_fmac_f32_e32 v164, v116, v116
	v_fmac_f32_e32 v165, v118, v118
	v_add_f32_e32 v124, v162, v163
	global_store_dwordx2 v[166:167], v[114:115], off
	global_store_dwordx4 v[168:169], v[120:123], off offset:64
	v_add_f32_e32 v114, v125, v127
	v_pk_mul_f32 v[154:155], v[90:91], v[122:123]
	v_pk_mul_f32 v[156:157], v[88:89], v[120:121]
	v_fmac_f32_e32 v170, v150, v150
	v_fmac_f32_e32 v171, v152, v152
	v_cvt_pk_bf16_f32 v112, v156, v157
	v_cvt_pk_bf16_f32 v113, v154, v155
	v_add_f32_e32 v115, v164, v165
	v_add_f32_e32 v114, v124, v114
	global_store_dwordx2 v[166:167], v[112:113], off offset:32
	global_store_dwordx4 v[168:169], v[116:119], off offset:512
	v_add_f32_e32 v113, v114, v115
	v_add_f32_e32 v114, v170, v171
	v_pk_mul_f32 v[160:161], v[80:81], v[116:117]
	v_add_f32_e32 v116, v113, v114
	ds_bpermute_b32 v117, v148, v116
	v_pk_mul_f32 v[158:159], v[82:83], v[118:119]
	v_cvt_pk_bf16_f32 v112, v160, v161
	v_pk_mul_f32 v[114:115], v[66:67], v[152:153]
	v_cvt_pk_bf16_f32 v113, v158, v159
	global_store_dwordx2 v[166:167], v[112:113], off offset:256
	global_store_dwordx4 v[168:169], v[150:153], off offset:576
	s_waitcnt lgkmcnt(0)
	v_add_f32_e32 v112, v116, v117
	ds_bpermute_b32 v113, v149, v112
	v_pk_mul_f32 v[116:117], v[64:65], v[150:151]
	s_nop 0
	v_cvt_pk_bf16_f32 v116, v116, v117
	v_cvt_pk_bf16_f32 v117, v114, v115
	global_store_dwordx2 v[166:167], v[116:117], off offset:288
	s_and_saveexec_b64 s[4:5], vcc
	s_cbranch_execz .LBB0_506
; __device__ __forceinline__ unsigned cvt_pk_bf16(float lo, float hi) { unsigned r; asm volatile("v_cvt_pk_bf16_f32 %0, %1, %2" : "=v"(r) : "v"(lo), "v"(hi)); return r; }
;     __device__ __forceinline__ void operator()(const f32x4 (&acc)[2][2][4][2], const Unit& u, int wr, int wc, int fr_, int fq_) const {
;     ...
;             for (int m = 0; m < 2; ++m) { const size_t off = (size_t)(row0 + ai * HALF + (2 * mh + m) * 16) * ldc + col0;
; #pragma unroll
;                 for (int bj = 0; bj < 2; ++bj)
; #pragma unroll
;                     for (int n = 0; n < 2; ++n) bs[m][bj][n] = *(const f32x4*)(base + off + bj * HALF + n * 16); }
;             asm volatile("" ::: "memory");
; #pragma unroll
;             for (int m = 0; m < 2; ++m) { const int row = row0 + ai * HALF + (2 * mh + m) * 16; const size_t off = (size_t)row * ldc + col0; float ss = 0.f;
; #pragma unroll
;                 for (int bj = 0; bj < 2; ++bj)
; #pragma unroll
;                     for (int n = 0; n < 2; ++n) { const f32x4 o = bs[m][bj][n] + gv[bj][n] * acc[ai][bj][2 * mh + m][n]; *(f32x4*)(out + off + bj * HALF + n * 16) = o;
;                         if constexpr (EMIT) { ss += (o[0] * o[0] + o[1] * o[1]) + (o[2] * o[2] + o[3] * o[3]); const f32x4 y = o * gm[bj][n];
;                             typedef unsigned u32x2_t __attribute__((ext_vector_type(2))); u32x2_t w; w.x = cvt_pk_bf16(y[0], y[1]); w.y = cvt_pk_bf16(y[2], y[3]); *(u32x2_t*)(A2 + off + bj * HALF + n * 16) = w; } }
;                 if constexpr (EMIT) { ss += __shfl_xor(ss, 16); ss += __shfl_xor(ss, 32); if (fq == 0) atomicAdd(ssq + row, (unsigned long long)(ss * 16777216.0f)); } }
;             asm volatile("" ::: "memory");
	s_waitcnt lgkmcnt(0)
	v_add_f32_e32 v112, v112, v113
	v_mul_f32_e32 v112, 0x4b800000, v112
	v_trunc_f32_e32 v112, v112
	v_mul_f32_e32 v113, 0x2f800000, v112
	v_floor_f32_e32 v113, v113
	v_fmac_f32_e32 v112, 0xcf800000, v113
	v_cvt_u32_f32_e32 v112, v112
	v_cvt_u32_f32_e32 v113, v113
	v_mov_b32_e32 v230, v112
	v_mov_b32_e32 v231, v113
.LBB0_506:
	s_or_b64 exec, exec, s[4:5]
	s_waitcnt lgkmcnt(0)
	v_lshlrev_b64 v[112:113], 11, v[144:145]
	v_lshl_add_u64 v[112:113], v[112:113], 0, v[188:189]
	v_pk_fma_f32 v[110:111], v[110:111], v[106:107], v[142:143]
	v_pk_fma_f32 v[108:109], v[108:109], v[104:105], v[140:141]
	v_lshl_add_u64 v[114:115], v[112:113], 2, s[10:11]
	v_mul_f32_e32 v116, v109, v109
	v_mul_f32_e32 v117, v111, v111
	global_store_dwordx4 v[114:115], v[108:111], off
	v_fmac_f32_e32 v116, v108, v108
	v_fmac_f32_e32 v117, v110, v110
	v_pk_mul_f32 v[110:111], v[102:103], v[110:111]
	v_pk_mul_f32 v[108:109], v[100:101], v[108:109]
	v_pk_fma_f32 v[96:97], v[96:97], v[92:93], v[136:137]
	v_cvt_pk_bf16_f32 v108, v108, v109
	v_cvt_pk_bf16_f32 v109, v110, v111
	v_lshl_add_u64 v[110:111], v[112:113], 1, s[16:17]
	global_store_dwordx2 v[110:111], v[108:109], off
	v_pk_fma_f32 v[98:99], v[98:99], v[94:95], v[138:139]
	v_mul_f32_e32 v108, v97, v97
	global_store_dwordx4 v[114:115], v[96:99], off offset:64
	v_fmac_f32_e32 v108, v96, v96
	v_mul_f32_e32 v109, v99, v99
	v_pk_mul_f32 v[96:97], v[88:89], v[96:97]
	v_fmac_f32_e32 v109, v98, v98
	v_pk_mul_f32 v[98:99], v[90:91], v[98:99]
	v_cvt_pk_bf16_f32 v96, v96, v97
	v_pk_fma_f32 v[78:79], v[78:79], v[86:87], v[134:135]
	v_cvt_pk_bf16_f32 v97, v98, v99
	v_pk_fma_f32 v[76:77], v[76:77], v[84:85], v[132:133]
	global_store_dwordx2 v[110:111], v[96:97], off offset:32
	v_mul_f32_e32 v96, v77, v77
	v_mul_f32_e32 v97, v79, v79
	v_add_f32_e32 v116, v116, v117
	v_add_f32_e32 v108, v108, v109
	v_fmac_f32_e32 v96, v76, v76
	v_fmac_f32_e32 v97, v78, v78
	v_add_f32_e32 v108, v116, v108
	global_store_dwordx4 v[114:115], v[76:79], off offset:512
	v_add_f32_e32 v96, v96, v97
	v_add_f32_e32 v99, v108, v96
	v_pk_mul_f32 v[76:77], v[80:81], v[76:77]
	v_pk_mul_f32 v[96:97], v[82:83], v[78:79]
	v_cvt_pk_bf16_f32 v98, v76, v77
	v_pk_fma_f32 v[78:79], v[70:71], v[74:75], v[130:131]
	v_pk_fma_f32 v[76:77], v[68:69], v[72:73], v[128:129]
	v_mul_f32_e32 v69, v79, v79
	v_mul_f32_e32 v68, v77, v77
	v_fmac_f32_e32 v68, v76, v76
	v_fmac_f32_e32 v69, v78, v78
	v_add_f32_e32 v68, v68, v69
	v_add_f32_e32 v68, v99, v68
	ds_bpermute_b32 v69, v148, v68
	v_cvt_pk_bf16_f32 v99, v96, v97
	global_store_dwordx2 v[110:111], v[98:99], off offset:256
	global_store_dwordx4 v[114:115], v[76:79], off offset:576
	v_pk_mul_f32 v[70:71], v[66:67], v[78:79]
	s_waitcnt lgkmcnt(0)
	v_add_f32_e32 v68, v68, v69
	ds_bpermute_b32 v69, v149, v68
	v_pk_mul_f32 v[76:77], v[64:65], v[76:77]
	s_nop 0
	v_cvt_pk_bf16_f32 v76, v76, v77
	v_cvt_pk_bf16_f32 v77, v70, v71
	global_store_dwordx2 v[110:111], v[76:77], off offset:288
	s_and_saveexec_b64 s[4:5], vcc
	s_cbranch_execz .LBB0_508
	s_waitcnt lgkmcnt(0)
	v_add_f32_e32 v68, v68, v69
	v_mul_f32_e32 v68, 0x4b800000, v68
	v_trunc_f32_e32 v68, v68
	v_mul_f32_e32 v69, 0x2f800000, v68
	v_floor_f32_e32 v69, v69
	v_fmac_f32_e32 v68, 0xcf800000, v69
	v_cvt_u32_f32_e32 v68, v68
	v_cvt_u32_f32_e32 v69, v69
	v_mov_b32_e32 v232, v68
	v_mov_b32_e32 v233, v69
.LBB0_508:
	s_or_b64 exec, exec, s[4:5]
	v_add_u32_e32 v114, 0x80, v192
	v_ashrrev_i32_e32 v115, 31, v114
	s_waitcnt lgkmcnt(0)
	v_lshlrev_b64 v[68:69], 13, v[114:115]
	v_lshl_add_u64 v[68:69], v[190:191], 0, v[68:69]
	global_load_dwordx4 v[116:119], v[68:69], off
	global_load_dwordx4 v[120:123], v[68:69], off offset:64
	global_load_dwordx4 v[124:127], v[68:69], off offset:512
	global_load_dwordx4 v[128:131], v[68:69], off offset:576
	v_add_u32_e32 v112, 0x90, v192
	v_ashrrev_i32_e32 v113, 31, v112
	v_lshlrev_b64 v[68:69], 13, v[112:113]
	v_lshl_add_u64 v[68:69], v[190:191], 0, v[68:69]
	global_load_dwordx4 v[108:111], v[68:69], off
	global_load_dwordx4 v[96:99], v[68:69], off offset:64
	global_load_dwordx4 v[76:79], v[68:69], off offset:512
	s_nop 0
	global_load_dwordx4 v[68:71], v[68:69], off offset:576
	v_lshlrev_b64 v[132:133], 11, v[114:115]
	v_lshl_add_u64 v[132:133], v[132:133], 0, v[188:189]
	v_lshl_add_u64 v[134:135], v[132:133], 2, s[10:11]
	v_lshl_add_u64 v[132:133], v[132:133], 1, s[16:17]
	s_waitcnt vmcnt(0) lgkmcnt(0)
	v_pk_fma_f32 v[62:63], v[62:63], v[106:107], v[118:119]
	v_pk_fma_f32 v[60:61], v[60:61], v[104:105], v[116:117]
	v_pk_fma_f32 v[58:59], v[58:59], v[94:95], v[122:123]
	v_pk_fma_f32 v[56:57], v[56:57], v[92:93], v[120:121]
	v_pk_fma_f32 v[54:55], v[54:55], v[86:87], v[126:127]
	v_pk_fma_f32 v[52:53], v[52:53], v[84:85], v[124:125]
	v_pk_fma_f32 v[118:119], v[50:51], v[74:75], v[130:131]
	v_pk_fma_f32 v[116:117], v[48:49], v[72:73], v[128:129]
	global_store_dwordx4 v[134:135], v[60:63], off
	v_mul_f32_e32 v128, v61, v61
	v_mul_f32_e32 v129, v63, v63
	v_pk_mul_f32 v[48:49], v[102:103], v[62:63]
	v_pk_mul_f32 v[50:51], v[100:101], v[60:61]
	v_mul_f32_e32 v61, v57, v57
	v_mul_f32_e32 v63, v59, v59
	v_mul_f32_e32 v130, v53, v53
	v_mul_f32_e32 v131, v55, v55
	v_fmac_f32_e32 v128, v60, v60
	v_fmac_f32_e32 v129, v62, v62
	v_cvt_pk_bf16_f32 v50, v50, v51
	v_cvt_pk_bf16_f32 v51, v48, v49
	v_fmac_f32_e32 v61, v56, v56
	v_fmac_f32_e32 v63, v58, v58
	v_mul_f32_e32 v136, v117, v117
	v_mul_f32_e32 v137, v119, v119
	v_fmac_f32_e32 v130, v52, v52
	v_fmac_f32_e32 v131, v54, v54
	v_add_f32_e32 v60, v128, v129
	global_store_dwordx2 v[132:133], v[50:51], off
	global_store_dwordx4 v[134:135], v[56:59], off offset:64
	v_add_f32_e32 v50, v61, v63
	v_pk_mul_f32 v[120:121], v[90:91], v[58:59]
	v_pk_mul_f32 v[122:123], v[88:89], v[56:57]
	v_fmac_f32_e32 v136, v116, v116
	v_fmac_f32_e32 v137, v118, v118
	v_cvt_pk_bf16_f32 v48, v122, v123
	v_cvt_pk_bf16_f32 v49, v120, v121
	v_add_f32_e32 v51, v130, v131
	v_add_f32_e32 v50, v60, v50
	global_store_dwordx2 v[132:133], v[48:49], off offset:32
	global_store_dwordx4 v[134:135], v[52:55], off offset:512
	v_add_f32_e32 v49, v50, v51
	v_add_f32_e32 v50, v136, v137
	v_pk_mul_f32 v[126:127], v[80:81], v[52:53]
	v_add_f32_e32 v52, v49, v50
	ds_bpermute_b32 v53, v148, v52
	v_pk_mul_f32 v[124:125], v[82:83], v[54:55]
	v_cvt_pk_bf16_f32 v48, v126, v127
	v_pk_mul_f32 v[50:51], v[66:67], v[118:119]
	v_cvt_pk_bf16_f32 v49, v124, v125
	global_store_dwordx2 v[132:133], v[48:49], off offset:256
	global_store_dwordx4 v[134:135], v[116:119], off offset:576
	s_waitcnt lgkmcnt(0)
	v_add_f32_e32 v48, v52, v53
	ds_bpermute_b32 v49, v149, v48
	v_pk_mul_f32 v[52:53], v[64:65], v[116:117]
	s_nop 0
	v_cvt_pk_bf16_f32 v52, v52, v53
	v_cvt_pk_bf16_f32 v53, v50, v51
	global_store_dwordx2 v[132:133], v[52:53], off offset:288
	s_and_saveexec_b64 s[4:5], vcc
	s_cbranch_execz .LBB0_510
; __device__ __forceinline__ unsigned cvt_pk_bf16(float lo, float hi) { unsigned r; asm volatile("v_cvt_pk_bf16_f32 %0, %1, %2" : "=v"(r) : "v"(lo), "v"(hi)); return r; }
;     __device__ __forceinline__ void operator()(const f32x4 (&acc)[2][2][4][2], const Unit& u, int wr, int wc, int fr_, int fq_) const {
;     ...
;             for (int m = 0; m < 2; ++m) { const size_t off = (size_t)(row0 + ai * HALF + (2 * mh + m) * 16) * ldc + col0;
; #pragma unroll
;                 for (int bj = 0; bj < 2; ++bj)
; #pragma unroll
;                     for (int n = 0; n < 2; ++n) bs[m][bj][n] = *(const f32x4*)(base + off + bj * HALF + n * 16); }
;             asm volatile("" ::: "memory");
; #pragma unroll
;             for (int m = 0; m < 2; ++m) { const int row = row0 + ai * HALF + (2 * mh + m) * 16; const size_t off = (size_t)row * ldc + col0; float ss = 0.f;
; #pragma unroll
;                 for (int bj = 0; bj < 2; ++bj)
; #pragma unroll
;                     for (int n = 0; n < 2; ++n) { const f32x4 o = bs[m][bj][n] + gv[bj][n] * acc[ai][bj][2 * mh + m][n]; *(f32x4*)(out + off + bj * HALF + n * 16) = o;
;                         if constexpr (EMIT) { ss += (o[0] * o[0] + o[1] * o[1]) + (o[2] * o[2] + o[3] * o[3]); const f32x4 y = o * gm[bj][n];
;                             typedef unsigned u32x2_t __attribute__((ext_vector_type(2))); u32x2_t w; w.x = cvt_pk_bf16(y[0], y[1]); w.y = cvt_pk_bf16(y[2], y[3]); *(u32x2_t*)(A2 + off + bj * HALF + n * 16) = w; } }
;                 if constexpr (EMIT) { ss += __shfl_xor(ss, 16); ss += __shfl_xor(ss, 32); if (fq == 0) atomicAdd(ssq + row, (unsigned long long)(ss * 16777216.0f)); } }
;             asm volatile("" ::: "memory");
	s_waitcnt lgkmcnt(0)
	v_add_f32_e32 v48, v48, v49
	v_mul_f32_e32 v48, 0x4b800000, v48
	v_trunc_f32_e32 v48, v48
	v_mul_f32_e32 v49, 0x2f800000, v48
	v_floor_f32_e32 v49, v49
	v_fmac_f32_e32 v48, 0xcf800000, v49
	v_cvt_u32_f32_e32 v48, v48
	v_cvt_u32_f32_e32 v49, v49
	v_mov_b32_e32 v234, v48
	v_mov_b32_e32 v235, v49
.LBB0_510:
	s_or_b64 exec, exec, s[4:5]
	s_waitcnt lgkmcnt(0)
	v_lshlrev_b64 v[48:49], 11, v[112:113]
	v_lshl_add_u64 v[48:49], v[48:49], 0, v[188:189]
	v_pk_fma_f32 v[46:47], v[46:47], v[106:107], v[110:111]
	v_pk_fma_f32 v[44:45], v[44:45], v[104:105], v[108:109]
	v_lshl_add_u64 v[50:51], v[48:49], 2, s[10:11]
	v_mul_f32_e32 v52, v45, v45
	v_mul_f32_e32 v53, v47, v47
	global_store_dwordx4 v[50:51], v[44:47], off
	v_fmac_f32_e32 v52, v44, v44
	v_fmac_f32_e32 v53, v46, v46
	v_pk_mul_f32 v[46:47], v[102:103], v[46:47]
	v_pk_mul_f32 v[44:45], v[100:101], v[44:45]
	v_pk_fma_f32 v[40:41], v[40:41], v[92:93], v[96:97]
	v_cvt_pk_bf16_f32 v44, v44, v45
	v_cvt_pk_bf16_f32 v45, v46, v47
	v_lshl_add_u64 v[46:47], v[48:49], 1, s[16:17]
	global_store_dwordx2 v[46:47], v[44:45], off
	v_pk_fma_f32 v[42:43], v[42:43], v[94:95], v[98:99]
	v_mul_f32_e32 v44, v41, v41
	global_store_dwordx4 v[50:51], v[40:43], off offset:64
	v_fmac_f32_e32 v44, v40, v40
	v_mul_f32_e32 v45, v43, v43
	v_pk_mul_f32 v[40:41], v[88:89], v[40:41]
	v_fmac_f32_e32 v45, v42, v42
	v_pk_mul_f32 v[42:43], v[90:91], v[42:43]
	v_cvt_pk_bf16_f32 v40, v40, v41
	v_pk_fma_f32 v[38:39], v[38:39], v[86:87], v[78:79]
	v_cvt_pk_bf16_f32 v41, v42, v43
	v_pk_fma_f32 v[36:37], v[36:37], v[84:85], v[76:77]
	global_store_dwordx2 v[46:47], v[40:41], off offset:32
	v_mul_f32_e32 v40, v37, v37
	v_mul_f32_e32 v41, v39, v39
	v_add_f32_e32 v52, v52, v53
	v_add_f32_e32 v44, v44, v45
	v_fmac_f32_e32 v40, v36, v36
	v_fmac_f32_e32 v41, v38, v38
	v_add_f32_e32 v44, v52, v44
	global_store_dwordx4 v[50:51], v[36:39], off offset:512
	v_add_f32_e32 v40, v40, v41
	v_add_f32_e32 v41, v44, v40
	v_pk_mul_f32 v[36:37], v[80:81], v[36:37]
	v_pk_mul_f32 v[38:39], v[82:83], v[38:39]
	v_cvt_pk_bf16_f32 v40, v36, v37
	v_pk_fma_f32 v[36:37], v[34:35], v[74:75], v[70:71]
	v_pk_fma_f32 v[34:35], v[32:33], v[72:73], v[68:69]
	v_mul_f32_e32 v33, v37, v37
	v_mul_f32_e32 v32, v35, v35
	v_fmac_f32_e32 v32, v34, v34
	v_fmac_f32_e32 v33, v36, v36
	v_add_f32_e32 v32, v32, v33
	v_add_f32_e32 v32, v41, v32
	ds_bpermute_b32 v33, v148, v32
	v_cvt_pk_bf16_f32 v41, v38, v39
	global_store_dwordx2 v[46:47], v[40:41], off offset:256
	global_store_dwordx4 v[50:51], v[34:37], off offset:576
	s_waitcnt lgkmcnt(0)
	v_add_f32_e32 v32, v32, v33
	ds_bpermute_b32 v33, v149, v32
	v_pk_mul_f32 v[34:35], v[64:65], v[34:35]
	v_pk_mul_f32 v[36:37], v[66:67], v[36:37]
	v_cvt_pk_bf16_f32 v34, v34, v35
	s_nop 0
	v_cvt_pk_bf16_f32 v35, v36, v37
	global_store_dwordx2 v[46:47], v[34:35], off offset:288
	s_and_saveexec_b64 s[4:5], vcc
	s_cbranch_execz .LBB0_512
	s_waitcnt lgkmcnt(0)
	v_add_f32_e32 v32, v32, v33
	v_mul_f32_e32 v32, 0x4b800000, v32
	v_trunc_f32_e32 v32, v32
	v_mul_f32_e32 v33, 0x2f800000, v32
	v_floor_f32_e32 v33, v33
	v_fmac_f32_e32 v32, 0xcf800000, v33
	v_cvt_u32_f32_e32 v32, v32
	v_cvt_u32_f32_e32 v33, v33
	v_mov_b32_e32 v236, v32
	v_mov_b32_e32 v237, v33
.LBB0_512:
	s_or_b64 exec, exec, s[4:5]
	v_add_u32_e32 v50, 0xa0, v192
	v_ashrrev_i32_e32 v51, 31, v50
	s_waitcnt lgkmcnt(0)
	v_lshlrev_b64 v[32:33], 13, v[50:51]
	v_lshl_add_u64 v[32:33], v[190:191], 0, v[32:33]
	global_load_dwordx4 v[52:55], v[32:33], off
	global_load_dwordx4 v[56:59], v[32:33], off offset:64
	global_load_dwordx4 v[60:63], v[32:33], off offset:512
	global_load_dwordx4 v[68:71], v[32:33], off offset:576
	v_add_u32_e32 v48, 0xb0, v192
	v_ashrrev_i32_e32 v49, 31, v48
	v_lshlrev_b64 v[32:33], 13, v[48:49]
	v_lshl_add_u64 v[32:33], v[190:191], 0, v[32:33]
	global_load_dwordx4 v[44:47], v[32:33], off
	global_load_dwordx4 v[40:43], v[32:33], off offset:64
	global_load_dwordx4 v[36:39], v[32:33], off offset:512
	s_nop 0
	global_load_dwordx4 v[32:35], v[32:33], off offset:576
	v_lshlrev_b64 v[76:77], 11, v[50:51]
	v_lshl_add_u64 v[76:77], v[76:77], 0, v[188:189]
	v_lshl_add_u64 v[78:79], v[76:77], 2, s[10:11]
	v_lshl_add_u64 v[76:77], v[76:77], 1, s[16:17]
	s_waitcnt vmcnt(0) lgkmcnt(0)
	v_pk_fma_f32 v[30:31], v[30:31], v[106:107], v[54:55]
	v_pk_fma_f32 v[28:29], v[28:29], v[104:105], v[52:53]
	v_pk_fma_f32 v[26:27], v[26:27], v[94:95], v[58:59]
	v_pk_fma_f32 v[24:25], v[24:25], v[92:93], v[56:57]
	v_pk_fma_f32 v[22:23], v[22:23], v[86:87], v[62:63]
	v_pk_fma_f32 v[20:21], v[20:21], v[84:85], v[60:61]
	v_pk_fma_f32 v[54:55], v[18:19], v[74:75], v[70:71]
	v_pk_fma_f32 v[52:53], v[16:17], v[72:73], v[68:69]
	global_store_dwordx4 v[78:79], v[28:31], off
	v_mul_f32_e32 v68, v29, v29
	v_mul_f32_e32 v69, v31, v31
	v_pk_mul_f32 v[16:17], v[102:103], v[30:31]
	v_pk_mul_f32 v[18:19], v[100:101], v[28:29]
	v_mul_f32_e32 v29, v25, v25
	v_mul_f32_e32 v31, v27, v27
	v_mul_f32_e32 v70, v21, v21
	v_mul_f32_e32 v71, v23, v23
	v_fmac_f32_e32 v68, v28, v28
	v_fmac_f32_e32 v69, v30, v30
	v_cvt_pk_bf16_f32 v18, v18, v19
	v_cvt_pk_bf16_f32 v19, v16, v17
	v_fmac_f32_e32 v29, v24, v24
	v_fmac_f32_e32 v31, v26, v26
	v_mul_f32_e32 v96, v53, v53
	v_mul_f32_e32 v97, v55, v55
	v_fmac_f32_e32 v70, v20, v20
	v_fmac_f32_e32 v71, v22, v22
	v_add_f32_e32 v28, v68, v69
	global_store_dwordx2 v[76:77], v[18:19], off
	global_store_dwordx4 v[78:79], v[24:27], off offset:64
	v_add_f32_e32 v18, v29, v31
	v_pk_mul_f32 v[56:57], v[90:91], v[26:27]
	v_pk_mul_f32 v[58:59], v[88:89], v[24:25]
	v_fmac_f32_e32 v96, v52, v52
	v_fmac_f32_e32 v97, v54, v54
	v_cvt_pk_bf16_f32 v16, v58, v59
	v_cvt_pk_bf16_f32 v17, v56, v57
	v_add_f32_e32 v19, v70, v71
	v_add_f32_e32 v18, v28, v18
	global_store_dwordx2 v[76:77], v[16:17], off offset:32
	global_store_dwordx4 v[78:79], v[20:23], off offset:512
	v_add_f32_e32 v17, v18, v19
	v_add_f32_e32 v18, v96, v97
	v_pk_mul_f32 v[62:63], v[80:81], v[20:21]
	v_add_f32_e32 v20, v17, v18
	ds_bpermute_b32 v21, v148, v20
	v_pk_mul_f32 v[60:61], v[82:83], v[22:23]
	v_cvt_pk_bf16_f32 v16, v62, v63
	v_pk_mul_f32 v[18:19], v[66:67], v[54:55]
	v_cvt_pk_bf16_f32 v17, v60, v61
	global_store_dwordx2 v[76:77], v[16:17], off offset:256
	global_store_dwordx4 v[78:79], v[52:55], off offset:576
	s_waitcnt lgkmcnt(0)
	v_add_f32_e32 v16, v20, v21
	ds_bpermute_b32 v17, v149, v16
	v_pk_mul_f32 v[20:21], v[64:65], v[52:53]
	s_nop 0
	v_cvt_pk_bf16_f32 v20, v20, v21
	v_cvt_pk_bf16_f32 v21, v18, v19
	global_store_dwordx2 v[76:77], v[20:21], off offset:288
	s_and_saveexec_b64 s[4:5], vcc
	s_cbranch_execz .LBB0_514
	s_waitcnt lgkmcnt(0)
	v_add_f32_e32 v16, v16, v17
	v_mul_f32_e32 v16, 0x4b800000, v16
	v_trunc_f32_e32 v16, v16
	v_mul_f32_e32 v17, 0x2f800000, v16
	v_floor_f32_e32 v17, v17
	v_fmac_f32_e32 v16, 0xcf800000, v17
	v_cvt_u32_f32_e32 v16, v16
	v_cvt_u32_f32_e32 v17, v17
	v_mov_b32_e32 v238, v16
	v_mov_b32_e32 v239, v17
; __device__ __forceinline__ unsigned cvt_pk_bf16(float lo, float hi) { unsigned r; asm volatile("v_cvt_pk_bf16_f32 %0, %1, %2" : "=v"(r) : "v"(lo), "v"(hi)); return r; }
;     __device__ __forceinline__ void operator()(const f32x4 (&acc)[2][2][4][2], const Unit& u, int wr, int wc, int fr_, int fq_) const {
;     ...
;             for (int m = 0; m < 2; ++m) { const int row = row0 + ai * HALF + (2 * mh + m) * 16; const size_t off = (size_t)row * ldc + col0; float ss = 0.f;
; #pragma unroll
;                 for (int bj = 0; bj < 2; ++bj)
; #pragma unroll
;                     for (int n = 0; n < 2; ++n) { const f32x4 o = bs[m][bj][n] + gv[bj][n] * acc[ai][bj][2 * mh + m][n]; *(f32x4*)(out + off + bj * HALF + n * 16) = o;
;                         if constexpr (EMIT) { ss += (o[0] * o[0] + o[1] * o[1]) + (o[2] * o[2] + o[3] * o[3]); const f32x4 y = o * gm[bj][n];
;                             typedef unsigned u32x2_t __attribute__((ext_vector_type(2))); u32x2_t w; w.x = cvt_pk_bf16(y[0], y[1]); w.y = cvt_pk_bf16(y[2], y[3]); *(u32x2_t*)(A2 + off + bj * HALF + n * 16) = w; } }
;                 if constexpr (EMIT) { ss += __shfl_xor(ss, 16); ss += __shfl_xor(ss, 32); if (fq == 0) atomicAdd(ssq + row, (unsigned long long)(ss * 16777216.0f)); } }
;             asm volatile("" ::: "memory");
.LBB0_514:
	s_or_b64 exec, exec, s[4:5]
	s_waitcnt lgkmcnt(0)
	v_lshlrev_b64 v[16:17], 11, v[48:49]
	v_lshl_add_u64 v[16:17], v[16:17], 0, v[188:189]
	v_pk_fma_f32 v[14:15], v[14:15], v[106:107], v[46:47]
	v_pk_fma_f32 v[12:13], v[12:13], v[104:105], v[44:45]
	v_lshl_add_u64 v[18:19], v[16:17], 2, s[10:11]
	v_mul_f32_e32 v20, v13, v13
	v_mul_f32_e32 v21, v15, v15
	global_store_dwordx4 v[18:19], v[12:15], off
	v_fmac_f32_e32 v20, v12, v12
	v_fmac_f32_e32 v21, v14, v14
	v_pk_mul_f32 v[14:15], v[102:103], v[14:15]
	v_pk_mul_f32 v[12:13], v[100:101], v[12:13]
	v_pk_fma_f32 v[8:9], v[8:9], v[92:93], v[40:41]
	v_cvt_pk_bf16_f32 v12, v12, v13
	v_cvt_pk_bf16_f32 v13, v14, v15
	v_lshl_add_u64 v[14:15], v[16:17], 1, s[16:17]
	global_store_dwordx2 v[14:15], v[12:13], off
	v_pk_fma_f32 v[10:11], v[10:11], v[94:95], v[42:43]
	v_mul_f32_e32 v12, v9, v9
	global_store_dwordx4 v[18:19], v[8:11], off offset:64
	v_fmac_f32_e32 v12, v8, v8
	v_mul_f32_e32 v13, v11, v11
	v_pk_mul_f32 v[8:9], v[88:89], v[8:9]
	v_fmac_f32_e32 v13, v10, v10
	v_pk_mul_f32 v[10:11], v[90:91], v[10:11]
	v_cvt_pk_bf16_f32 v8, v8, v9
	v_pk_fma_f32 v[6:7], v[6:7], v[86:87], v[38:39]
	v_cvt_pk_bf16_f32 v9, v10, v11
	v_pk_fma_f32 v[4:5], v[4:5], v[84:85], v[36:37]
	global_store_dwordx2 v[14:15], v[8:9], off offset:32
	v_mul_f32_e32 v8, v5, v5
	v_mul_f32_e32 v9, v7, v7
	v_add_f32_e32 v20, v20, v21
	v_add_f32_e32 v12, v12, v13
	v_fmac_f32_e32 v8, v4, v4
	v_fmac_f32_e32 v9, v6, v6
	v_add_f32_e32 v12, v20, v12
	global_store_dwordx4 v[18:19], v[4:7], off offset:512
	v_add_f32_e32 v8, v8, v9
	v_add_f32_e32 v9, v12, v8
	v_pk_mul_f32 v[4:5], v[80:81], v[4:5]
	v_pk_mul_f32 v[6:7], v[82:83], v[6:7]
	v_cvt_pk_bf16_f32 v8, v4, v5
	v_pk_fma_f32 v[4:5], v[2:3], v[74:75], v[34:35]
	v_pk_fma_f32 v[2:3], v[0:1], v[72:73], v[32:33]
	v_mul_f32_e32 v1, v5, v5
	v_mul_f32_e32 v0, v3, v3
	v_fmac_f32_e32 v0, v2, v2
	v_fmac_f32_e32 v1, v4, v4
	v_add_f32_e32 v0, v0, v1
	v_add_f32_e32 v0, v9, v0
	ds_bpermute_b32 v1, v148, v0
	v_cvt_pk_bf16_f32 v9, v6, v7
	global_store_dwordx2 v[14:15], v[8:9], off offset:256
	global_store_dwordx4 v[18:19], v[2:5], off offset:576
	s_waitcnt lgkmcnt(0)
	v_add_f32_e32 v0, v0, v1
	ds_bpermute_b32 v1, v149, v0
	v_pk_mul_f32 v[2:3], v[64:65], v[2:3]
	v_pk_mul_f32 v[4:5], v[66:67], v[4:5]
	v_cvt_pk_bf16_f32 v2, v2, v3
	s_nop 0
	v_cvt_pk_bf16_f32 v3, v4, v5
	global_store_dwordx2 v[14:15], v[2:3], off offset:288
	s_and_saveexec_b64 s[4:5], vcc
	s_cbranch_execz .LBB0_516
	s_waitcnt lgkmcnt(0)
	v_add_f32_e32 v0, v0, v1
	v_mul_f32_e32 v0, 0x4b800000, v0
	v_trunc_f32_e32 v0, v0
	v_mul_f32_e32 v1, 0x2f800000, v0
	v_floor_f32_e32 v1, v1
	v_fmac_f32_e32 v0, 0xcf800000, v1
	v_cvt_u32_f32_e32 v0, v0
	v_cvt_u32_f32_e32 v1, v1
	v_mov_b32_e32 v240, v0
	v_mov_b32_e32 v241, v1
	global_atomic_add_x2 v[242:243], v[226:227], off
	global_atomic_add_x2 v[242:243], v[228:229], off offset:128
	global_atomic_add_x2 v[242:243], v[230:231], off offset:256
	global_atomic_add_x2 v[242:243], v[232:233], off offset:384
	global_atomic_add_x2 v[242:243], v[234:235], off offset:1024
	global_atomic_add_x2 v[242:243], v[236:237], off offset:1152
	global_atomic_add_x2 v[242:243], v[238:239], off offset:1280
	global_atomic_add_x2 v[242:243], v[240:241], off offset:1408

; __device__ __forceinline__ int lane_asm() { int l; asm volatile("v_mbcnt_lo_u32_b32 %0, -1, 0\n\tv_mbcnt_hi_u32_b32 %0, -1, %0" : "=v"(l)); return l; }
;     __device__ __forceinline__ void operator()(const f32x4 (&acc)[2][2][4][2], const Unit& u, int wr, int wc, int fr_, int fq_) const {
;         const int l_ = lane_asm(); const int fr = l_ & 15, fq = l_ >> 4; (void)fr_; (void)fq_;
;         const int row0 = u.pm * BM + wr * 64 + fr, col0 = u.pn * BM + wc * 32 + 4 * fq;
;         f32x4 gv[2][2], gm[2][2];
; #pragma unroll
;         for (int bj = 0; bj < 2; ++bj)
; #pragma unroll
;             for (int n = 0; n < 2; ++n) { gv[bj][n] = *(const f32x4*)(gate + col0 + bj * HALF + n * 16);
;                 if constexpr (EMIT) gm[bj][n] = *(const f32x4*)(gmv + col0 + bj * HALF + n * 16); else gm[bj][n] = gv[bj][n]; }
; #pragma unroll
;         for (int ai = 0; ai < 2; ++ai)
; #pragma unroll
;         for (int mh = 0; mh < 2; ++mh) {
;             f32x4 bs[2][2][2];
; #pragma unroll
;             for (int m = 0; m < 2; ++m) { const size_t off = (size_t)(row0 + ai * HALF + (2 * mh + m) * 16) * ldc + col0;
; #pragma unroll
;                 for (int bj = 0; bj < 2; ++bj)
; #pragma unroll
;                     for (int n = 0; n < 2; ++n) bs[m][bj][n] = *(const f32x4*)(base + off + bj * HALF + n * 16); }
;             asm volatile("" ::: "memory");
; #pragma unroll
;             for (int m = 0; m < 2; ++m) { const int row = row0 + ai * HALF + (2 * mh + m) * 16; const size_t off = (size_t)row * ldc + col0; float ss = 0.f;
; #pragma unroll
;                 for (int bj = 0; bj < 2; ++bj)
; #pragma unroll
;                     for (int n = 0; n < 2; ++n) { const f32x4 o = bs[m][bj][n] + gv[bj][n] * acc[ai][bj][2 * mh + m][n]; *(f32x4*)(out + off + bj * HALF + n * 16) = o;
;                         if constexpr (EMIT) { ss += (o[0] * o[0] + o[1] * o[1]) + (o[2] * o[2] + o[3] * o[3]); const f32x4 y = o * gm[bj][n];
;                             typedef unsigned u32x2_t __attribute__((ext_vector_type(2))); u32x2_t w; w.x = cvt_pk_bf16(y[0], y[1]); w.y = cvt_pk_bf16(y[2], y[3]); *(u32x2_t*)(A2 + off + bj * HALF + n * 16) = w; } }
;                 if constexpr (EMIT) { ss += __shfl_xor(ss, 16); ss += __shfl_xor(ss, 32); if (fq == 0) atomicAdd(ssq + row, (unsigned long long)(ss * 16777216.0f)); } }
.LBB0_1307:
	v_mbcnt_lo_u32_b32 v203, -1, 0
	v_mbcnt_hi_u32_b32 v203, -1, v203
	s_lshl_b32 s4, s4, 8
	v_ashrrev_i32_e32 v64, 2, v203
	s_lshl_b32 s5, s34, 8
	s_or_b32 s4, s4, s50
	v_and_b32_e32 v64, -4, v64
	s_add_i32 s5, s5, s49
	v_add_u32_e32 v188, s4, v64
	v_ashrrev_i32_e32 v189, 31, v188
	v_and_or_b32 v192, v203, 15, s5
	v_lshlrev_b64 v[64:65], 2, v[188:189]
	v_ashrrev_i32_e32 v193, 31, v192
	v_lshl_add_u64 v[190:191], s[8:9], 0, v[64:65]
	v_lshlrev_b64 v[72:73], 13, v[192:193]
	v_lshl_add_u64 v[220:221], v[190:191], 0, v[72:73]
	v_lshl_add_u64 v[66:67], s[12:13], 0, v[64:65]
	global_load_dwordx4 v[204:207], v[220:221], off
	global_load_dwordx4 v[104:107], v[66:67], off
	global_load_dwordx4 v[92:95], v[66:67], off offset:64
	global_load_dwordx4 v[208:211], v[220:221], off offset:64
	global_load_dwordx4 v[212:215], v[220:221], off offset:512
	global_load_dwordx4 v[84:87], v[66:67], off offset:512
	global_load_dwordx4 v[72:75], v[66:67], off offset:576
	global_load_dwordx4 v[216:219], v[220:221], off offset:576
	v_lshl_add_u64 v[64:65], s[16:17], 0, v[64:65]
	global_load_dwordx4 v[100:103], v[64:65], off
	global_load_dwordx4 v[88:91], v[64:65], off offset:64
	global_load_dwordx4 v[80:83], v[64:65], off offset:512
	s_nop 0
	global_load_dwordx4 v[64:67], v[64:65], off offset:576
	v_or_b32_e32 v194, 16, v192
	v_ashrrev_i32_e32 v195, 31, v194
	v_lshlrev_b64 v[160:161], 13, v[194:195]
	v_lshl_add_u64 v[196:197], v[190:191], 0, v[160:161]
	global_load_dwordx4 v[172:175], v[196:197], off
	global_load_dwordx4 v[168:171], v[196:197], off offset:64
	global_load_dwordx4 v[164:167], v[196:197], off offset:512
	global_load_dwordx4 v[160:163], v[196:197], off offset:576
	v_and_b32_e32 v223, 64, v202
	v_xor_b32_e32 v222, 16, v202
	v_add_u32_e32 v224, 64, v223
	v_cmp_lt_i32_e64 s[4:5], v222, v224
	v_cmp_gt_u32_e32 vcc, 16, v203
	s_waitcnt vmcnt(0) lgkmcnt(0)
	v_pk_fma_f32 v[158:159], v[158:159], v[106:107], v[206:207]
	v_cndmask_b32_e64 v203, v202, v222, s[4:5]
	v_lshlrev_b64 v[222:223], 11, v[192:193]
	v_pk_fma_f32 v[156:157], v[156:157], v[104:105], v[204:205]
	v_pk_fma_f32 v[154:155], v[154:155], v[94:95], v[210:211]
	v_pk_fma_f32 v[152:153], v[152:153], v[92:93], v[208:209]
	v_lshl_add_u64 v[222:223], v[222:223], 0, v[188:189]
	v_pk_fma_f32 v[150:151], v[150:151], v[86:87], v[214:215]
	v_pk_fma_f32 v[148:149], v[148:149], v[84:85], v[212:213]
	v_pk_fma_f32 v[206:207], v[146:147], v[74:75], v[218:219]
	v_pk_fma_f32 v[204:205], v[144:145], v[72:73], v[216:217]
	global_store_dwordx4 v[220:221], v[156:159], off
	v_mul_f32_e32 v218, v157, v157
	v_mul_f32_e32 v219, v159, v159
	v_pk_mul_f32 v[144:145], v[102:103], v[158:159]
	v_pk_mul_f32 v[146:147], v[100:101], v[156:157]
	v_mul_f32_e32 v157, v153, v153
	v_mul_f32_e32 v159, v155, v155
	v_lshl_add_u64 v[222:223], v[222:223], 1, s[14:15]
	v_mul_f32_e32 v225, v149, v149
	v_mul_f32_e32 v226, v151, v151
	v_fmac_f32_e32 v218, v156, v156
	v_fmac_f32_e32 v219, v158, v158
	v_cvt_pk_bf16_f32 v146, v146, v147
	v_cvt_pk_bf16_f32 v147, v144, v145
	v_fmac_f32_e32 v157, v152, v152
	v_fmac_f32_e32 v159, v154, v154
	v_mul_f32_e32 v227, v205, v205
	v_mul_f32_e32 v228, v207, v207
	v_fmac_f32_e32 v225, v148, v148
	v_fmac_f32_e32 v226, v150, v150
	v_add_f32_e32 v156, v218, v219
	global_store_dwordx2 v[222:223], v[146:147], off
	global_store_dwordx4 v[220:221], v[152:155], off offset:64
	v_add_f32_e32 v146, v157, v159
	v_pk_mul_f32 v[208:209], v[90:91], v[154:155]
	v_pk_mul_f32 v[210:211], v[88:89], v[152:153]
	v_fmac_f32_e32 v227, v204, v204
	v_fmac_f32_e32 v228, v206, v206
	v_cvt_pk_bf16_f32 v144, v210, v211
	v_cvt_pk_bf16_f32 v145, v208, v209
	v_add_f32_e32 v147, v225, v226
	v_add_f32_e32 v146, v156, v146
	v_add_f32_e32 v152, v227, v228
	global_store_dwordx2 v[222:223], v[144:145], off offset:32
	global_store_dwordx4 v[220:221], v[148:151], off offset:512
	v_add_f32_e32 v144, v146, v147
	v_lshlrev_b32_e32 v203, 2, v203
	v_add_f32_e32 v146, v144, v152
	ds_bpermute_b32 v147, v203, v146
	v_pk_mul_f32 v[212:213], v[82:83], v[150:151]
	v_pk_mul_f32 v[214:215], v[80:81], v[148:149]
	v_pk_mul_f32 v[216:217], v[66:67], v[206:207]
	v_cvt_pk_bf16_f32 v144, v214, v215
	v_cvt_pk_bf16_f32 v145, v212, v213
	global_store_dwordx2 v[222:223], v[144:145], off offset:256
	global_store_dwordx4 v[220:221], v[204:207], off offset:576
	v_xor_b32_e32 v145, 32, v202
	v_cmp_lt_i32_e64 s[4:5], v145, v224
	s_waitcnt lgkmcnt(0)
	v_add_f32_e32 v144, v146, v147
	v_pk_mul_f32 v[146:147], v[64:65], v[204:205]
	v_cndmask_b32_e64 v145, v202, v145, s[4:5]
	v_lshlrev_b32_e32 v150, 2, v145
	ds_bpermute_b32 v145, v150, v144
	v_cvt_pk_bf16_f32 v146, v146, v147
	v_cvt_pk_bf16_f32 v147, v216, v217
	global_store_dwordx2 v[222:223], v[146:147], off offset:288
	s_and_saveexec_b64 s[4:5], vcc
	s_cbranch_execz .LBB0_1309
	s_waitcnt lgkmcnt(0)
	v_add_f32_e32 v144, v144, v145
	v_mul_f32_e32 v144, 0x4b800000, v144
	v_trunc_f32_e32 v144, v144
	v_mul_f32_e32 v145, 0x2f800000, v144
	v_floor_f32_e32 v145, v145
	v_fmac_f32_e32 v144, 0xcf800000, v145
	v_cvt_u32_f32_e32 v144, v144
	v_cvt_u32_f32_e32 v145, v145
	v_mov_b32_e32 v230, v144
	v_mov_b32_e32 v231, v145
	v_lshl_add_u64 v[246:247], v[192:193], 3, s[18:19]
; __device__ __forceinline__ unsigned cvt_pk_bf16(float lo, float hi) { unsigned r; asm volatile("v_cvt_pk_bf16_f32 %0, %1, %2" : "=v"(r) : "v"(lo), "v"(hi)); return r; }
;     __device__ __forceinline__ void operator()(const f32x4 (&acc)[2][2][4][2], const Unit& u, int wr, int wc, int fr_, int fq_) const {
;     ...
;             for (int m = 0; m < 2; ++m) { const size_t off = (size_t)(row0 + ai * HALF + (2 * mh + m) * 16) * ldc + col0;
; #pragma unroll
;                 for (int bj = 0; bj < 2; ++bj)
; #pragma unroll
;                     for (int n = 0; n < 2; ++n) bs[m][bj][n] = *(const f32x4*)(base + off + bj * HALF + n * 16); }
;             asm volatile("" ::: "memory");
; #pragma unroll
;             for (int m = 0; m < 2; ++m) { const int row = row0 + ai * HALF + (2 * mh + m) * 16; const size_t off = (size_t)row * ldc + col0; float ss = 0.f;
; #pragma unroll
;                 for (int bj = 0; bj < 2; ++bj)
; #pragma unroll
;                     for (int n = 0; n < 2; ++n) { const f32x4 o = bs[m][bj][n] + gv[bj][n] * acc[ai][bj][2 * mh + m][n]; *(f32x4*)(out + off + bj * HALF + n * 16) = o;
;                         if constexpr (EMIT) { ss += (o[0] * o[0] + o[1] * o[1]) + (o[2] * o[2] + o[3] * o[3]); const f32x4 y = o * gm[bj][n];
;                             typedef unsigned u32x2_t __attribute__((ext_vector_type(2))); u32x2_t w; w.x = cvt_pk_bf16(y[0], y[1]); w.y = cvt_pk_bf16(y[2], y[3]); *(u32x2_t*)(A2 + off + bj * HALF + n * 16) = w; } }
;                 if constexpr (EMIT) { ss += __shfl_xor(ss, 16); ss += __shfl_xor(ss, 32); if (fq == 0) atomicAdd(ssq + row, (unsigned long long)(ss * 16777216.0f)); } }
;             asm volatile("" ::: "memory");
.LBB0_1309:
	s_or_b64 exec, exec, s[4:5]
	v_pk_fma_f32 v[142:143], v[142:143], v[106:107], v[174:175]
	v_pk_fma_f32 v[140:141], v[140:141], v[104:105], v[172:173]
	s_waitcnt lgkmcnt(0)
	v_lshlrev_b64 v[144:145], 11, v[194:195]
	v_mul_f32_e32 v146, v141, v141
	v_mul_f32_e32 v147, v143, v143
	v_lshl_add_u64 v[144:145], v[144:145], 0, v[188:189]
	global_store_dwordx4 v[196:197], v[140:143], off
	v_fmac_f32_e32 v146, v140, v140
	v_fmac_f32_e32 v147, v142, v142
	v_pk_mul_f32 v[142:143], v[102:103], v[142:143]
	v_pk_mul_f32 v[140:141], v[100:101], v[140:141]
	v_pk_fma_f32 v[136:137], v[136:137], v[92:93], v[168:169]
	v_cvt_pk_bf16_f32 v140, v140, v141
	v_cvt_pk_bf16_f32 v141, v142, v143
	v_lshl_add_u64 v[142:143], v[144:145], 1, s[14:15]
	global_store_dwordx2 v[142:143], v[140:141], off
	v_pk_fma_f32 v[138:139], v[138:139], v[94:95], v[170:171]
	v_mul_f32_e32 v140, v137, v137
	global_store_dwordx4 v[196:197], v[136:139], off offset:64
	v_fmac_f32_e32 v140, v136, v136
	v_mul_f32_e32 v141, v139, v139
	v_pk_mul_f32 v[136:137], v[88:89], v[136:137]
	v_fmac_f32_e32 v141, v138, v138
	v_pk_mul_f32 v[138:139], v[90:91], v[138:139]
	v_cvt_pk_bf16_f32 v136, v136, v137
	v_pk_fma_f32 v[134:135], v[134:135], v[86:87], v[166:167]
	v_cvt_pk_bf16_f32 v137, v138, v139
	v_pk_fma_f32 v[132:133], v[132:133], v[84:85], v[164:165]
	global_store_dwordx2 v[142:143], v[136:137], off offset:32
	v_mul_f32_e32 v136, v133, v133
	v_mul_f32_e32 v137, v135, v135
	v_add_f32_e32 v146, v146, v147
	v_add_f32_e32 v140, v140, v141
	v_fmac_f32_e32 v136, v132, v132
	v_fmac_f32_e32 v137, v134, v134
	v_add_f32_e32 v140, v146, v140
	global_store_dwordx4 v[196:197], v[132:135], off offset:512
	v_add_f32_e32 v136, v136, v137
	v_add_f32_e32 v137, v140, v136
	v_pk_mul_f32 v[132:133], v[80:81], v[132:133]
	v_pk_mul_f32 v[134:135], v[82:83], v[134:135]
	v_cvt_pk_bf16_f32 v136, v132, v133
	v_pk_fma_f32 v[132:133], v[130:131], v[74:75], v[162:163]
	v_pk_fma_f32 v[130:131], v[128:129], v[72:73], v[160:161]
	v_mul_f32_e32 v129, v133, v133
	v_mul_f32_e32 v128, v131, v131
	v_fmac_f32_e32 v128, v130, v130
	v_fmac_f32_e32 v129, v132, v132
	v_add_f32_e32 v128, v128, v129
	v_add_f32_e32 v128, v137, v128
	ds_bpermute_b32 v129, v203, v128
	v_cvt_pk_bf16_f32 v137, v134, v135
	global_store_dwordx2 v[142:143], v[136:137], off offset:256
	global_store_dwordx4 v[196:197], v[130:133], off offset:576
	s_waitcnt lgkmcnt(0)
	v_add_f32_e32 v128, v128, v129
	ds_bpermute_b32 v129, v150, v128
	v_pk_mul_f32 v[130:131], v[64:65], v[130:131]
	v_pk_mul_f32 v[132:133], v[66:67], v[132:133]
	v_cvt_pk_bf16_f32 v130, v130, v131
	s_nop 0
	v_cvt_pk_bf16_f32 v131, v132, v133
	global_store_dwordx2 v[142:143], v[130:131], off offset:288
	s_and_saveexec_b64 s[4:5], vcc
	s_cbranch_execz .LBB0_1311
	s_waitcnt lgkmcnt(0)
	v_add_f32_e32 v128, v128, v129
	v_mul_f32_e32 v128, 0x4b800000, v128
	v_trunc_f32_e32 v128, v128
	v_mul_f32_e32 v129, 0x2f800000, v128
	v_floor_f32_e32 v129, v129
	v_fmac_f32_e32 v128, 0xcf800000, v129
	v_cvt_u32_f32_e32 v128, v128
	v_cvt_u32_f32_e32 v129, v129
	v_mov_b32_e32 v232, v128
	v_mov_b32_e32 v233, v129
.LBB0_1311:
	s_or_b64 exec, exec, s[4:5]
	v_or_b32_e32 v148, 32, v192
	v_ashrrev_i32_e32 v149, 31, v148
	s_waitcnt lgkmcnt(0)
	v_lshlrev_b64 v[128:129], 13, v[148:149]
	v_lshl_add_u64 v[168:169], v[190:191], 0, v[128:129]
	global_load_dwordx4 v[152:155], v[168:169], off
	global_load_dwordx4 v[156:159], v[168:169], off offset:64
	global_load_dwordx4 v[160:163], v[168:169], off offset:512
	global_load_dwordx4 v[164:167], v[168:169], off offset:576
	v_or_b32_e32 v144, 48, v192
	v_ashrrev_i32_e32 v145, 31, v144
	v_lshlrev_b64 v[128:129], 13, v[144:145]
	v_lshl_add_u64 v[146:147], v[190:191], 0, v[128:129]
	global_load_dwordx4 v[140:143], v[146:147], off
	global_load_dwordx4 v[136:139], v[146:147], off offset:64
	global_load_dwordx4 v[132:135], v[146:147], off offset:512
	global_load_dwordx4 v[128:131], v[146:147], off offset:576
	v_lshlrev_b64 v[170:171], 11, v[148:149]
	v_lshl_add_u64 v[170:171], v[170:171], 0, v[188:189]
	v_lshl_add_u64 v[170:171], v[170:171], 1, s[14:15]
	s_waitcnt vmcnt(0) lgkmcnt(0)
	v_pk_fma_f32 v[126:127], v[126:127], v[106:107], v[154:155]
	v_pk_fma_f32 v[124:125], v[124:125], v[104:105], v[152:153]
	v_pk_fma_f32 v[122:123], v[122:123], v[94:95], v[158:159]
	v_pk_fma_f32 v[120:121], v[120:121], v[92:93], v[156:157]
	v_pk_fma_f32 v[118:119], v[118:119], v[86:87], v[162:163]
	v_pk_fma_f32 v[116:117], v[116:117], v[84:85], v[160:161]
	v_pk_fma_f32 v[154:155], v[114:115], v[74:75], v[166:167]
	v_pk_fma_f32 v[152:153], v[112:113], v[72:73], v[164:165]
	global_store_dwordx4 v[168:169], v[124:127], off
	v_mul_f32_e32 v151, v125, v125
	v_mul_f32_e32 v164, v127, v127
	v_pk_mul_f32 v[112:113], v[102:103], v[126:127]
	v_pk_mul_f32 v[114:115], v[100:101], v[124:125]
	v_mul_f32_e32 v125, v121, v121
	v_mul_f32_e32 v127, v123, v123
	v_mul_f32_e32 v165, v117, v117
	v_mul_f32_e32 v166, v119, v119
	v_fmac_f32_e32 v151, v124, v124
	v_fmac_f32_e32 v164, v126, v126
	v_cvt_pk_bf16_f32 v114, v114, v115
	v_cvt_pk_bf16_f32 v115, v112, v113
	v_fmac_f32_e32 v125, v120, v120
	v_fmac_f32_e32 v127, v122, v122
	v_mul_f32_e32 v167, v153, v153
	v_mul_f32_e32 v172, v155, v155
	v_fmac_f32_e32 v165, v116, v116
	v_fmac_f32_e32 v166, v118, v118
	v_add_f32_e32 v124, v151, v164
	global_store_dwordx2 v[170:171], v[114:115], off
	global_store_dwordx4 v[168:169], v[120:123], off offset:64
	v_add_f32_e32 v114, v125, v127
	v_pk_mul_f32 v[156:157], v[90:91], v[122:123]
	v_pk_mul_f32 v[158:159], v[88:89], v[120:121]
	v_fmac_f32_e32 v167, v152, v152
	v_fmac_f32_e32 v172, v154, v154
	v_cvt_pk_bf16_f32 v112, v158, v159
	v_cvt_pk_bf16_f32 v113, v156, v157
	v_add_f32_e32 v115, v165, v166
	v_add_f32_e32 v114, v124, v114
	global_store_dwordx2 v[170:171], v[112:113], off offset:32
	global_store_dwordx4 v[168:169], v[116:119], off offset:512
	v_add_f32_e32 v113, v114, v115
	v_add_f32_e32 v114, v167, v172
	v_pk_mul_f32 v[162:163], v[80:81], v[116:117]
	v_add_f32_e32 v116, v113, v114
	ds_bpermute_b32 v117, v203, v116
	v_pk_mul_f32 v[160:161], v[82:83], v[118:119]
	v_cvt_pk_bf16_f32 v112, v162, v163
	v_pk_mul_f32 v[114:115], v[66:67], v[154:155]
	v_cvt_pk_bf16_f32 v113, v160, v161
	global_store_dwordx2 v[170:171], v[112:113], off offset:256
	global_store_dwordx4 v[168:169], v[152:155], off offset:576
	s_waitcnt lgkmcnt(0)
	v_add_f32_e32 v112, v116, v117
	ds_bpermute_b32 v113, v150, v112
	v_pk_mul_f32 v[116:117], v[64:65], v[152:153]
	s_nop 0
	v_cvt_pk_bf16_f32 v116, v116, v117
	v_cvt_pk_bf16_f32 v117, v114, v115
	global_store_dwordx2 v[170:171], v[116:117], off offset:288
	s_and_saveexec_b64 s[4:5], vcc
	s_cbranch_execz .LBB0_1313
	s_waitcnt lgkmcnt(0)
	v_add_f32_e32 v112, v112, v113
	v_mul_f32_e32 v112, 0x4b800000, v112
	v_trunc_f32_e32 v112, v112
	v_mul_f32_e32 v113, 0x2f800000, v112
	v_floor_f32_e32 v113, v113
	v_fmac_f32_e32 v112, 0xcf800000, v113
	v_cvt_u32_f32_e32 v112, v112
	v_cvt_u32_f32_e32 v113, v113
	v_mov_b32_e32 v234, v112
	v_mov_b32_e32 v235, v113
; __device__ __forceinline__ unsigned cvt_pk_bf16(float lo, float hi) { unsigned r; asm volatile("v_cvt_pk_bf16_f32 %0, %1, %2" : "=v"(r) : "v"(lo), "v"(hi)); return r; }
;     __device__ __forceinline__ void operator()(const f32x4 (&acc)[2][2][4][2], const Unit& u, int wr, int wc, int fr_, int fq_) const {
;     ...
;             for (int m = 0; m < 2; ++m) { const size_t off = (size_t)(row0 + ai * HALF + (2 * mh + m) * 16) * ldc + col0;
; #pragma unroll
;                 for (int bj = 0; bj < 2; ++bj)
; #pragma unroll
;                     for (int n = 0; n < 2; ++n) bs[m][bj][n] = *(const f32x4*)(base + off + bj * HALF + n * 16); }
;             asm volatile("" ::: "memory");
; #pragma unroll
;             for (int m = 0; m < 2; ++m) { const int row = row0 + ai * HALF + (2 * mh + m) * 16; const size_t off = (size_t)row * ldc + col0; float ss = 0.f;
; #pragma unroll
;                 for (int bj = 0; bj < 2; ++bj)
; #pragma unroll
;                     for (int n = 0; n < 2; ++n) { const f32x4 o = bs[m][bj][n] + gv[bj][n] * acc[ai][bj][2 * mh + m][n]; *(f32x4*)(out + off + bj * HALF + n * 16) = o;
;                         if constexpr (EMIT) { ss += (o[0] * o[0] + o[1] * o[1]) + (o[2] * o[2] + o[3] * o[3]); const f32x4 y = o * gm[bj][n];
;                             typedef unsigned u32x2_t __attribute__((ext_vector_type(2))); u32x2_t w; w.x = cvt_pk_bf16(y[0], y[1]); w.y = cvt_pk_bf16(y[2], y[3]); *(u32x2_t*)(A2 + off + bj * HALF + n * 16) = w; } }
;                 if constexpr (EMIT) { ss += __shfl_xor(ss, 16); ss += __shfl_xor(ss, 32); if (fq == 0) atomicAdd(ssq + row, (unsigned long long)(ss * 16777216.0f)); } }
;             asm volatile("" ::: "memory");
.LBB0_1313:
	s_or_b64 exec, exec, s[4:5]
	v_pk_fma_f32 v[110:111], v[110:111], v[106:107], v[142:143]
	v_pk_fma_f32 v[108:109], v[108:109], v[104:105], v[140:141]
	s_waitcnt lgkmcnt(0)
	v_lshlrev_b64 v[112:113], 11, v[144:145]
	v_mul_f32_e32 v114, v109, v109
	v_mul_f32_e32 v115, v111, v111
	v_lshl_add_u64 v[112:113], v[112:113], 0, v[188:189]
	global_store_dwordx4 v[146:147], v[108:111], off
	v_fmac_f32_e32 v114, v108, v108
	v_fmac_f32_e32 v115, v110, v110
	v_pk_mul_f32 v[110:111], v[102:103], v[110:111]
	v_pk_mul_f32 v[108:109], v[100:101], v[108:109]
	v_pk_fma_f32 v[96:97], v[96:97], v[92:93], v[136:137]
	v_cvt_pk_bf16_f32 v108, v108, v109
	v_cvt_pk_bf16_f32 v109, v110, v111
	v_lshl_add_u64 v[110:111], v[112:113], 1, s[14:15]
	global_store_dwordx2 v[110:111], v[108:109], off
	v_pk_fma_f32 v[98:99], v[98:99], v[94:95], v[138:139]
	v_mul_f32_e32 v108, v97, v97
	global_store_dwordx4 v[146:147], v[96:99], off offset:64
	v_fmac_f32_e32 v108, v96, v96
	v_mul_f32_e32 v109, v99, v99
	v_pk_mul_f32 v[96:97], v[88:89], v[96:97]
	v_fmac_f32_e32 v109, v98, v98
	v_pk_mul_f32 v[98:99], v[90:91], v[98:99]
	v_cvt_pk_bf16_f32 v96, v96, v97
	v_pk_fma_f32 v[78:79], v[78:79], v[86:87], v[134:135]
	v_cvt_pk_bf16_f32 v97, v98, v99
	v_pk_fma_f32 v[76:77], v[76:77], v[84:85], v[132:133]
	global_store_dwordx2 v[110:111], v[96:97], off offset:32
	v_mul_f32_e32 v96, v77, v77
	v_mul_f32_e32 v97, v79, v79
	v_add_f32_e32 v114, v114, v115
	v_add_f32_e32 v108, v108, v109
	v_fmac_f32_e32 v96, v76, v76
	v_fmac_f32_e32 v97, v78, v78
	v_add_f32_e32 v108, v114, v108
	global_store_dwordx4 v[146:147], v[76:79], off offset:512
	v_add_f32_e32 v96, v96, v97
	v_add_f32_e32 v99, v108, v96
	v_pk_mul_f32 v[76:77], v[80:81], v[76:77]
	v_pk_mul_f32 v[96:97], v[82:83], v[78:79]
	v_cvt_pk_bf16_f32 v98, v76, v77
	v_pk_fma_f32 v[78:79], v[70:71], v[74:75], v[130:131]
	v_pk_fma_f32 v[76:77], v[68:69], v[72:73], v[128:129]
	v_mul_f32_e32 v69, v79, v79
	v_mul_f32_e32 v68, v77, v77
	v_fmac_f32_e32 v68, v76, v76
	v_fmac_f32_e32 v69, v78, v78
	v_add_f32_e32 v68, v68, v69
	v_add_f32_e32 v68, v99, v68
	ds_bpermute_b32 v69, v203, v68
	v_cvt_pk_bf16_f32 v99, v96, v97
	global_store_dwordx2 v[110:111], v[98:99], off offset:256
	global_store_dwordx4 v[146:147], v[76:79], off offset:576
	v_pk_mul_f32 v[70:71], v[66:67], v[78:79]
	s_waitcnt lgkmcnt(0)
	v_add_f32_e32 v68, v68, v69
	ds_bpermute_b32 v69, v150, v68
	v_pk_mul_f32 v[76:77], v[64:65], v[76:77]
	s_nop 0
	v_cvt_pk_bf16_f32 v76, v76, v77
	v_cvt_pk_bf16_f32 v77, v70, v71
	global_store_dwordx2 v[110:111], v[76:77], off offset:288
	s_and_saveexec_b64 s[4:5], vcc
	s_cbranch_execz .LBB0_1315
	s_waitcnt lgkmcnt(0)
	v_add_f32_e32 v68, v68, v69
	v_mul_f32_e32 v68, 0x4b800000, v68
	v_trunc_f32_e32 v68, v68
	v_mul_f32_e32 v69, 0x2f800000, v68
	v_floor_f32_e32 v69, v69
	v_fmac_f32_e32 v68, 0xcf800000, v69
	v_cvt_u32_f32_e32 v68, v68
	v_cvt_u32_f32_e32 v69, v69
	v_mov_b32_e32 v236, v68
	v_mov_b32_e32 v237, v69
.LBB0_1315:
	s_or_b64 exec, exec, s[4:5]
	v_add_u32_e32 v116, 0x80, v192
	v_ashrrev_i32_e32 v117, 31, v116
	s_waitcnt lgkmcnt(0)
	v_lshlrev_b64 v[68:69], 13, v[116:117]
	v_lshl_add_u64 v[134:135], v[190:191], 0, v[68:69]
	global_load_dwordx4 v[118:121], v[134:135], off
	global_load_dwordx4 v[122:125], v[134:135], off offset:64
	global_load_dwordx4 v[126:129], v[134:135], off offset:512
	global_load_dwordx4 v[130:133], v[134:135], off offset:576
	v_add_u32_e32 v112, 0x90, v192
	v_ashrrev_i32_e32 v113, 31, v112
	v_lshlrev_b64 v[68:69], 13, v[112:113]
	v_lshl_add_u64 v[114:115], v[190:191], 0, v[68:69]
	global_load_dwordx4 v[108:111], v[114:115], off
	global_load_dwordx4 v[96:99], v[114:115], off offset:64
	global_load_dwordx4 v[76:79], v[114:115], off offset:512
	global_load_dwordx4 v[68:71], v[114:115], off offset:576
	v_lshlrev_b64 v[136:137], 11, v[116:117]
	v_lshl_add_u64 v[136:137], v[136:137], 0, v[188:189]
	v_lshl_add_u64 v[136:137], v[136:137], 1, s[14:15]
	s_waitcnt vmcnt(0) lgkmcnt(0)
	v_pk_fma_f32 v[62:63], v[62:63], v[106:107], v[120:121]
	v_pk_fma_f32 v[60:61], v[60:61], v[104:105], v[118:119]
	v_pk_fma_f32 v[58:59], v[58:59], v[94:95], v[124:125]
	v_pk_fma_f32 v[56:57], v[56:57], v[92:93], v[122:123]
	v_pk_fma_f32 v[54:55], v[54:55], v[86:87], v[128:129]
	v_pk_fma_f32 v[52:53], v[52:53], v[84:85], v[126:127]
	v_pk_fma_f32 v[120:121], v[50:51], v[74:75], v[132:133]
	v_pk_fma_f32 v[118:119], v[48:49], v[72:73], v[130:131]
	global_store_dwordx4 v[134:135], v[60:63], off
	v_mul_f32_e32 v130, v61, v61
	v_mul_f32_e32 v131, v63, v63
	v_pk_mul_f32 v[48:49], v[102:103], v[62:63]
	v_pk_mul_f32 v[50:51], v[100:101], v[60:61]
	v_mul_f32_e32 v61, v57, v57
	v_mul_f32_e32 v63, v59, v59
	v_mul_f32_e32 v132, v53, v53
	v_mul_f32_e32 v133, v55, v55
	v_fmac_f32_e32 v130, v60, v60
	v_fmac_f32_e32 v131, v62, v62
	v_cvt_pk_bf16_f32 v50, v50, v51
	v_cvt_pk_bf16_f32 v51, v48, v49
	v_fmac_f32_e32 v61, v56, v56
	v_fmac_f32_e32 v63, v58, v58
	v_mul_f32_e32 v138, v119, v119
	v_mul_f32_e32 v139, v121, v121
	v_fmac_f32_e32 v132, v52, v52
	v_fmac_f32_e32 v133, v54, v54
	v_add_f32_e32 v60, v130, v131
	global_store_dwordx2 v[136:137], v[50:51], off
	global_store_dwordx4 v[134:135], v[56:59], off offset:64
	v_add_f32_e32 v50, v61, v63
	v_pk_mul_f32 v[122:123], v[90:91], v[58:59]
	v_pk_mul_f32 v[124:125], v[88:89], v[56:57]
	v_fmac_f32_e32 v138, v118, v118
	v_fmac_f32_e32 v139, v120, v120
	v_cvt_pk_bf16_f32 v48, v124, v125
	v_cvt_pk_bf16_f32 v49, v122, v123
	v_add_f32_e32 v51, v132, v133
	v_add_f32_e32 v50, v60, v50
	global_store_dwordx2 v[136:137], v[48:49], off offset:32
	global_store_dwordx4 v[134:135], v[52:55], off offset:512
	v_add_f32_e32 v49, v50, v51
	v_add_f32_e32 v50, v138, v139
	v_pk_mul_f32 v[128:129], v[80:81], v[52:53]
	v_add_f32_e32 v52, v49, v50
	ds_bpermute_b32 v53, v203, v52
	v_pk_mul_f32 v[126:127], v[82:83], v[54:55]
	v_cvt_pk_bf16_f32 v48, v128, v129
	v_pk_mul_f32 v[50:51], v[66:67], v[120:121]
	v_cvt_pk_bf16_f32 v49, v126, v127
	global_store_dwordx2 v[136:137], v[48:49], off offset:256
	global_store_dwordx4 v[134:135], v[118:121], off offset:576
	s_waitcnt lgkmcnt(0)
	v_add_f32_e32 v48, v52, v53
	ds_bpermute_b32 v49, v150, v48
	v_pk_mul_f32 v[52:53], v[64:65], v[118:119]
	s_nop 0
	v_cvt_pk_bf16_f32 v52, v52, v53
	v_cvt_pk_bf16_f32 v53, v50, v51
	global_store_dwordx2 v[136:137], v[52:53], off offset:288
	s_and_saveexec_b64 s[4:5], vcc
	s_cbranch_execz .LBB0_1317
	s_waitcnt lgkmcnt(0)
	v_add_f32_e32 v48, v48, v49
	v_mul_f32_e32 v48, 0x4b800000, v48
	v_trunc_f32_e32 v48, v48
	v_mul_f32_e32 v49, 0x2f800000, v48
	v_floor_f32_e32 v49, v49
	v_fmac_f32_e32 v48, 0xcf800000, v49
	v_cvt_u32_f32_e32 v48, v48
	v_cvt_u32_f32_e32 v49, v49
	v_mov_b32_e32 v238, v48
	v_mov_b32_e32 v239, v49
; __device__ __forceinline__ unsigned cvt_pk_bf16(float lo, float hi) { unsigned r; asm volatile("v_cvt_pk_bf16_f32 %0, %1, %2" : "=v"(r) : "v"(lo), "v"(hi)); return r; }
;     __device__ __forceinline__ void operator()(const f32x4 (&acc)[2][2][4][2], const Unit& u, int wr, int wc, int fr_, int fq_) const {
;     ...
;             for (int m = 0; m < 2; ++m) { const size_t off = (size_t)(row0 + ai * HALF + (2 * mh + m) * 16) * ldc + col0;
; #pragma unroll
;                 for (int bj = 0; bj < 2; ++bj)
; #pragma unroll
;                     for (int n = 0; n < 2; ++n) bs[m][bj][n] = *(const f32x4*)(base + off + bj * HALF + n * 16); }
;             asm volatile("" ::: "memory");
; #pragma unroll
;             for (int m = 0; m < 2; ++m) { const int row = row0 + ai * HALF + (2 * mh + m) * 16; const size_t off = (size_t)row * ldc + col0; float ss = 0.f;
; #pragma unroll
;                 for (int bj = 0; bj < 2; ++bj)
; #pragma unroll
;                     for (int n = 0; n < 2; ++n) { const f32x4 o = bs[m][bj][n] + gv[bj][n] * acc[ai][bj][2 * mh + m][n]; *(f32x4*)(out + off + bj * HALF + n * 16) = o;
;                         if constexpr (EMIT) { ss += (o[0] * o[0] + o[1] * o[1]) + (o[2] * o[2] + o[3] * o[3]); const f32x4 y = o * gm[bj][n];
;                             typedef unsigned u32x2_t __attribute__((ext_vector_type(2))); u32x2_t w; w.x = cvt_pk_bf16(y[0], y[1]); w.y = cvt_pk_bf16(y[2], y[3]); *(u32x2_t*)(A2 + off + bj * HALF + n * 16) = w; } }
;                 if constexpr (EMIT) { ss += __shfl_xor(ss, 16); ss += __shfl_xor(ss, 32); if (fq == 0) atomicAdd(ssq + row, (unsigned long long)(ss * 16777216.0f)); } }
;             asm volatile("" ::: "memory");
.LBB0_1317:
	s_or_b64 exec, exec, s[4:5]
	v_pk_fma_f32 v[46:47], v[46:47], v[106:107], v[110:111]
	v_pk_fma_f32 v[44:45], v[44:45], v[104:105], v[108:109]
	s_waitcnt lgkmcnt(0)
	v_lshlrev_b64 v[48:49], 11, v[112:113]
	v_mul_f32_e32 v50, v45, v45
	v_mul_f32_e32 v51, v47, v47
	v_lshl_add_u64 v[48:49], v[48:49], 0, v[188:189]
	global_store_dwordx4 v[114:115], v[44:47], off
	v_fmac_f32_e32 v50, v44, v44
	v_fmac_f32_e32 v51, v46, v46
	v_pk_mul_f32 v[46:47], v[102:103], v[46:47]
	v_pk_mul_f32 v[44:45], v[100:101], v[44:45]
	v_pk_fma_f32 v[40:41], v[40:41], v[92:93], v[96:97]
	v_cvt_pk_bf16_f32 v44, v44, v45
	v_cvt_pk_bf16_f32 v45, v46, v47
	v_lshl_add_u64 v[46:47], v[48:49], 1, s[14:15]
	global_store_dwordx2 v[46:47], v[44:45], off
	v_pk_fma_f32 v[42:43], v[42:43], v[94:95], v[98:99]
	v_mul_f32_e32 v44, v41, v41
	global_store_dwordx4 v[114:115], v[40:43], off offset:64
	v_fmac_f32_e32 v44, v40, v40
	v_mul_f32_e32 v45, v43, v43
	v_pk_mul_f32 v[40:41], v[88:89], v[40:41]
	v_fmac_f32_e32 v45, v42, v42
	v_pk_mul_f32 v[42:43], v[90:91], v[42:43]
	v_cvt_pk_bf16_f32 v40, v40, v41
	v_pk_fma_f32 v[38:39], v[38:39], v[86:87], v[78:79]
	v_cvt_pk_bf16_f32 v41, v42, v43
	v_pk_fma_f32 v[36:37], v[36:37], v[84:85], v[76:77]
	global_store_dwordx2 v[46:47], v[40:41], off offset:32
	v_mul_f32_e32 v40, v37, v37
	v_mul_f32_e32 v41, v39, v39
	v_add_f32_e32 v50, v50, v51
	v_add_f32_e32 v44, v44, v45
	v_fmac_f32_e32 v40, v36, v36
	v_fmac_f32_e32 v41, v38, v38
	v_add_f32_e32 v44, v50, v44
	global_store_dwordx4 v[114:115], v[36:39], off offset:512
	v_add_f32_e32 v40, v40, v41
	v_add_f32_e32 v41, v44, v40
	v_pk_mul_f32 v[36:37], v[80:81], v[36:37]
	v_pk_mul_f32 v[38:39], v[82:83], v[38:39]
	v_cvt_pk_bf16_f32 v40, v36, v37
	v_pk_fma_f32 v[36:37], v[34:35], v[74:75], v[70:71]
	v_pk_fma_f32 v[34:35], v[32:33], v[72:73], v[68:69]
	v_mul_f32_e32 v33, v37, v37
	v_mul_f32_e32 v32, v35, v35
	v_fmac_f32_e32 v32, v34, v34
	v_fmac_f32_e32 v33, v36, v36
	v_add_f32_e32 v32, v32, v33
	v_add_f32_e32 v32, v41, v32
	ds_bpermute_b32 v33, v203, v32
	v_cvt_pk_bf16_f32 v41, v38, v39
	global_store_dwordx2 v[46:47], v[40:41], off offset:256
	global_store_dwordx4 v[114:115], v[34:37], off offset:576
	s_waitcnt lgkmcnt(0)
	v_add_f32_e32 v32, v32, v33
	ds_bpermute_b32 v33, v150, v32
	v_pk_mul_f32 v[34:35], v[64:65], v[34:35]
	v_pk_mul_f32 v[36:37], v[66:67], v[36:37]
	v_cvt_pk_bf16_f32 v34, v34, v35
	s_nop 0
	v_cvt_pk_bf16_f32 v35, v36, v37
	global_store_dwordx2 v[46:47], v[34:35], off offset:288
	s_and_saveexec_b64 s[4:5], vcc
	s_cbranch_execz .LBB0_1319
	s_waitcnt lgkmcnt(0)
	v_add_f32_e32 v32, v32, v33
	v_mul_f32_e32 v32, 0x4b800000, v32
	v_trunc_f32_e32 v32, v32
	v_mul_f32_e32 v33, 0x2f800000, v32
	v_floor_f32_e32 v33, v33
	v_fmac_f32_e32 v32, 0xcf800000, v33
	v_cvt_u32_f32_e32 v32, v32
	v_cvt_u32_f32_e32 v33, v33
	v_mov_b32_e32 v240, v32
	v_mov_b32_e32 v241, v33
.LBB0_1319:
	s_or_b64 exec, exec, s[4:5]
	v_add_u32_e32 v52, 0xa0, v192
	v_ashrrev_i32_e32 v53, 31, v52
	s_waitcnt lgkmcnt(0)
	v_lshlrev_b64 v[32:33], 13, v[52:53]
	v_lshl_add_u64 v[62:63], v[190:191], 0, v[32:33]
	global_load_dwordx4 v[54:57], v[62:63], off
	global_load_dwordx4 v[58:61], v[62:63], off offset:64
	global_load_dwordx4 v[68:71], v[62:63], off offset:512
	global_load_dwordx4 v[76:79], v[62:63], off offset:576
	v_add_u32_e32 v48, 0xb0, v192
	v_ashrrev_i32_e32 v49, 31, v48
	v_lshlrev_b64 v[32:33], 13, v[48:49]
	v_lshl_add_u64 v[50:51], v[190:191], 0, v[32:33]
	global_load_dwordx4 v[44:47], v[50:51], off
	global_load_dwordx4 v[40:43], v[50:51], off offset:64
	global_load_dwordx4 v[36:39], v[50:51], off offset:512
	global_load_dwordx4 v[32:35], v[50:51], off offset:576
	v_lshlrev_b64 v[96:97], 11, v[52:53]
	v_lshl_add_u64 v[96:97], v[96:97], 0, v[188:189]
	v_lshl_add_u64 v[96:97], v[96:97], 1, s[14:15]
	s_waitcnt vmcnt(0) lgkmcnt(0)
	v_pk_fma_f32 v[30:31], v[30:31], v[106:107], v[56:57]
	v_pk_fma_f32 v[28:29], v[28:29], v[104:105], v[54:55]
	v_pk_fma_f32 v[26:27], v[26:27], v[94:95], v[60:61]
	v_pk_fma_f32 v[24:25], v[24:25], v[92:93], v[58:59]
	v_pk_fma_f32 v[22:23], v[22:23], v[86:87], v[70:71]
	v_pk_fma_f32 v[20:21], v[20:21], v[84:85], v[68:69]
	v_pk_fma_f32 v[56:57], v[18:19], v[74:75], v[78:79]
	v_pk_fma_f32 v[54:55], v[16:17], v[72:73], v[76:77]
	global_store_dwordx4 v[62:63], v[28:31], off
	v_mul_f32_e32 v76, v29, v29
	v_mul_f32_e32 v77, v31, v31
	v_pk_mul_f32 v[16:17], v[102:103], v[30:31]
	v_pk_mul_f32 v[18:19], v[100:101], v[28:29]
	v_mul_f32_e32 v29, v25, v25
	v_mul_f32_e32 v31, v27, v27
	v_mul_f32_e32 v78, v21, v21
	v_mul_f32_e32 v79, v23, v23
	v_fmac_f32_e32 v76, v28, v28
	v_fmac_f32_e32 v77, v30, v30
	v_cvt_pk_bf16_f32 v18, v18, v19
	v_cvt_pk_bf16_f32 v19, v16, v17
	v_fmac_f32_e32 v29, v24, v24
	v_fmac_f32_e32 v31, v26, v26
	v_mul_f32_e32 v98, v55, v55
	v_mul_f32_e32 v99, v57, v57
	v_fmac_f32_e32 v78, v20, v20
	v_fmac_f32_e32 v79, v22, v22
	v_add_f32_e32 v28, v76, v77
	global_store_dwordx2 v[96:97], v[18:19], off
	global_store_dwordx4 v[62:63], v[24:27], off offset:64
	v_add_f32_e32 v18, v29, v31
	v_pk_mul_f32 v[58:59], v[90:91], v[26:27]
	v_pk_mul_f32 v[60:61], v[88:89], v[24:25]
	v_fmac_f32_e32 v98, v54, v54
	v_fmac_f32_e32 v99, v56, v56
	v_cvt_pk_bf16_f32 v16, v60, v61
	v_cvt_pk_bf16_f32 v17, v58, v59
	v_add_f32_e32 v19, v78, v79
	v_add_f32_e32 v18, v28, v18
	global_store_dwordx2 v[96:97], v[16:17], off offset:32
	global_store_dwordx4 v[62:63], v[20:23], off offset:512
	v_add_f32_e32 v17, v18, v19
	v_add_f32_e32 v18, v98, v99
	v_pk_mul_f32 v[70:71], v[80:81], v[20:21]
	v_add_f32_e32 v20, v17, v18
	ds_bpermute_b32 v21, v203, v20
	v_pk_mul_f32 v[68:69], v[82:83], v[22:23]
	v_cvt_pk_bf16_f32 v16, v70, v71
	v_pk_mul_f32 v[18:19], v[66:67], v[56:57]
	v_cvt_pk_bf16_f32 v17, v68, v69
	global_store_dwordx2 v[96:97], v[16:17], off offset:256
	global_store_dwordx4 v[62:63], v[54:57], off offset:576
	s_waitcnt lgkmcnt(0)
	v_add_f32_e32 v16, v20, v21
	ds_bpermute_b32 v17, v150, v16
	v_pk_mul_f32 v[20:21], v[64:65], v[54:55]
	s_nop 0
	v_cvt_pk_bf16_f32 v20, v20, v21
	v_cvt_pk_bf16_f32 v21, v18, v19
	global_store_dwordx2 v[96:97], v[20:21], off offset:288
	s_and_saveexec_b64 s[4:5], vcc
	s_cbranch_execz .LBB0_1321
	s_waitcnt lgkmcnt(0)
	v_add_f32_e32 v16, v16, v17
	v_mul_f32_e32 v16, 0x4b800000, v16
	v_trunc_f32_e32 v16, v16
	v_mul_f32_e32 v17, 0x2f800000, v16
	v_floor_f32_e32 v17, v17
	v_fmac_f32_e32 v16, 0xcf800000, v17
	v_cvt_u32_f32_e32 v16, v16
	v_cvt_u32_f32_e32 v17, v17
	v_mov_b32_e32 v242, v16
	v_mov_b32_e32 v243, v17
; __device__ __forceinline__ unsigned cvt_pk_bf16(float lo, float hi) { unsigned r; asm volatile("v_cvt_pk_bf16_f32 %0, %1, %2" : "=v"(r) : "v"(lo), "v"(hi)); return r; }
;     __device__ __forceinline__ void operator()(const f32x4 (&acc)[2][2][4][2], const Unit& u, int wr, int wc, int fr_, int fq_) const {
;     ...
;             for (int m = 0; m < 2; ++m) { const int row = row0 + ai * HALF + (2 * mh + m) * 16; const size_t off = (size_t)row * ldc + col0; float ss = 0.f;
; #pragma unroll
;                 for (int bj = 0; bj < 2; ++bj)
; #pragma unroll
;                     for (int n = 0; n < 2; ++n) { const f32x4 o = bs[m][bj][n] + gv[bj][n] * acc[ai][bj][2 * mh + m][n]; *(f32x4*)(out + off + bj * HALF + n * 16) = o;
;                         if constexpr (EMIT) { ss += (o[0] * o[0] + o[1] * o[1]) + (o[2] * o[2] + o[3] * o[3]); const f32x4 y = o * gm[bj][n];
;                             typedef unsigned u32x2_t __attribute__((ext_vector_type(2))); u32x2_t w; w.x = cvt_pk_bf16(y[0], y[1]); w.y = cvt_pk_bf16(y[2], y[3]); *(u32x2_t*)(A2 + off + bj * HALF + n * 16) = w; } }
;                 if constexpr (EMIT) { ss += __shfl_xor(ss, 16); ss += __shfl_xor(ss, 32); if (fq == 0) atomicAdd(ssq + row, (unsigned long long)(ss * 16777216.0f)); } }
;             asm volatile("" ::: "memory");
.LBB0_1321:
	s_or_b64 exec, exec, s[4:5]
	v_pk_fma_f32 v[14:15], v[14:15], v[106:107], v[46:47]
	v_pk_fma_f32 v[12:13], v[12:13], v[104:105], v[44:45]
	s_waitcnt lgkmcnt(0)
	v_lshlrev_b64 v[16:17], 11, v[48:49]
	v_mul_f32_e32 v18, v13, v13
	v_mul_f32_e32 v19, v15, v15
	v_lshl_add_u64 v[16:17], v[16:17], 0, v[188:189]
	global_store_dwordx4 v[50:51], v[12:15], off
	v_fmac_f32_e32 v18, v12, v12
	v_fmac_f32_e32 v19, v14, v14
	v_pk_mul_f32 v[14:15], v[102:103], v[14:15]
	v_pk_mul_f32 v[12:13], v[100:101], v[12:13]
	v_pk_fma_f32 v[8:9], v[8:9], v[92:93], v[40:41]
	v_cvt_pk_bf16_f32 v12, v12, v13
	v_cvt_pk_bf16_f32 v13, v14, v15
	v_lshl_add_u64 v[14:15], v[16:17], 1, s[14:15]
	global_store_dwordx2 v[14:15], v[12:13], off
	v_pk_fma_f32 v[10:11], v[10:11], v[94:95], v[42:43]
	v_mul_f32_e32 v12, v9, v9
	global_store_dwordx4 v[50:51], v[8:11], off offset:64
	v_fmac_f32_e32 v12, v8, v8
	v_mul_f32_e32 v13, v11, v11
	v_pk_mul_f32 v[8:9], v[88:89], v[8:9]
	v_fmac_f32_e32 v13, v10, v10
	v_pk_mul_f32 v[10:11], v[90:91], v[10:11]
	v_cvt_pk_bf16_f32 v8, v8, v9
	v_pk_fma_f32 v[6:7], v[6:7], v[86:87], v[38:39]
	v_cvt_pk_bf16_f32 v9, v10, v11
	v_pk_fma_f32 v[4:5], v[4:5], v[84:85], v[36:37]
	global_store_dwordx2 v[14:15], v[8:9], off offset:32
	v_mul_f32_e32 v8, v5, v5
	v_mul_f32_e32 v9, v7, v7
	v_add_f32_e32 v18, v18, v19
	v_add_f32_e32 v12, v12, v13
	v_fmac_f32_e32 v8, v4, v4
	v_fmac_f32_e32 v9, v6, v6
	v_add_f32_e32 v12, v18, v12
	global_store_dwordx4 v[50:51], v[4:7], off offset:512
	v_add_f32_e32 v8, v8, v9
	v_add_f32_e32 v9, v12, v8
	v_pk_mul_f32 v[4:5], v[80:81], v[4:5]
	v_pk_mul_f32 v[6:7], v[82:83], v[6:7]
	v_cvt_pk_bf16_f32 v8, v4, v5
	v_pk_fma_f32 v[4:5], v[2:3], v[74:75], v[34:35]
	v_pk_fma_f32 v[2:3], v[0:1], v[72:73], v[32:33]
	v_mul_f32_e32 v1, v5, v5
	v_mul_f32_e32 v0, v3, v3
	v_fmac_f32_e32 v0, v2, v2
	v_fmac_f32_e32 v1, v4, v4
	v_add_f32_e32 v0, v0, v1
	v_add_f32_e32 v0, v9, v0
	ds_bpermute_b32 v1, v203, v0
	v_cvt_pk_bf16_f32 v9, v6, v7
	global_store_dwordx2 v[14:15], v[8:9], off offset:256
	global_store_dwordx4 v[50:51], v[2:5], off offset:576
	s_waitcnt lgkmcnt(0)
	v_add_f32_e32 v0, v0, v1
	ds_bpermute_b32 v1, v150, v0
	v_pk_mul_f32 v[2:3], v[64:65], v[2:3]
	v_pk_mul_f32 v[4:5], v[66:67], v[4:5]
	v_cvt_pk_bf16_f32 v2, v2, v3
	s_nop 0
	v_cvt_pk_bf16_f32 v3, v4, v5
	global_store_dwordx2 v[14:15], v[2:3], off offset:288
	s_and_saveexec_b64 s[4:5], vcc
	s_cbranch_execz .LBB0_1323
	s_waitcnt lgkmcnt(0)
	v_add_f32_e32 v0, v0, v1
	v_mul_f32_e32 v0, 0x4b800000, v0
	v_trunc_f32_e32 v0, v0
	v_mul_f32_e32 v1, 0x2f800000, v0
	v_floor_f32_e32 v1, v1
	v_fmac_f32_e32 v0, 0xcf800000, v1
	v_cvt_u32_f32_e32 v0, v0
	v_cvt_u32_f32_e32 v1, v1
	v_mov_b32_e32 v244, v0
	v_mov_b32_e32 v245, v1
	global_atomic_add_x2 v[246:247], v[230:231], off
	global_atomic_add_x2 v[246:247], v[232:233], off offset:128
	global_atomic_add_x2 v[246:247], v[234:235], off offset:256
	global_atomic_add_x2 v[246:247], v[236:237], off offset:384
	global_atomic_add_x2 v[246:247], v[238:239], off offset:1024
	global_atomic_add_x2 v[246:247], v[240:241], off offset:1152
	global_atomic_add_x2 v[246:247], v[242:243], off offset:1280
	global_atomic_add_x2 v[246:247], v[244:245], off offset:1408
